# baseline (speedup 1.0000x reference)
.LBB0_11:
	s_cmpk_gt_i32 s75, 0xaff
	s_mov_b64 s[0:1], -1
	s_cbranch_scc0 .LBB0_109
	s_cmpk_gt_u32 s75, 0xeff
	s_cbranch_scc0 .LBB0_106
	s_cmpk_gt_u32 s75, 0x16ff
	s_cbranch_scc0 .LBB0_79
	s_cmpk_gt_u32 s75, 0x1eff
	s_cbranch_scc0 .LBB0_76
	s_cmpk_gt_u32 s75, 0x2eff
	s_cbranch_scc0 .LBB0_73
	s_cmpk_gt_u32 s75, 0x4eff
	s_cbranch_scc0 .LBB0_46
	s_cmpk_gt_u32 s75, 0x6eff
	s_cbranch_scc0 .LBB0_43
	s_and_b32 s0, s75, 0x7fffffc0
	s_add_i32 s72, s0, 0xffff9100
	s_and_b32 s2, s75, 63
	v_or_b32_e32 v2, s72, v56
	s_lshl_b32 s0, s2, 7
	s_mov_b32 s1, s73
	v_or_b32_e32 v48, 10, v2
	v_mov_b32_e32 v49, v3
	v_or_b32_e32 v50, 12, v2
	v_mov_b32_e32 v51, v3
	v_lshl_add_u64 v[36:37], v[4:5], 0, s[0:1]
	v_lshlrev_b64 v[38:39], 13, v[2:3]
	v_or_b32_e32 v40, 2, v2
	v_mov_b32_e32 v41, v3
	v_or_b32_e32 v42, 4, v2
	v_mov_b32_e32 v43, v3
	v_or_b32_e32 v44, 6, v2
	v_mov_b32_e32 v45, v3
	v_or_b32_e32 v46, 8, v2
	v_mov_b32_e32 v47, v3
	v_lshlrev_b64 v[48:49], 13, v[48:49]
	v_lshlrev_b64 v[50:51], 13, v[50:51]
	v_or_b32_e32 v52, 14, v2
	v_mov_b32_e32 v53, v3
	v_lshl_add_u64 v[38:39], v[36:37], 0, v[38:39]
	v_lshlrev_b64 v[40:41], 13, v[40:41]
	v_lshlrev_b64 v[42:43], 13, v[42:43]
	v_lshlrev_b64 v[44:45], 13, v[44:45]
	v_lshlrev_b64 v[46:47], 13, v[46:47]
	v_lshl_add_u64 v[48:49], v[36:37], 0, v[48:49]
	v_lshl_add_u64 v[50:51], v[36:37], 0, v[50:51]
	v_lshlrev_b64 v[52:53], 13, v[52:53]
	v_lshl_add_u64 v[40:41], v[36:37], 0, v[40:41]
	v_lshl_add_u64 v[42:43], v[36:37], 0, v[42:43]
	v_lshl_add_u64 v[44:45], v[36:37], 0, v[44:45]
	v_lshl_add_u64 v[46:47], v[36:37], 0, v[46:47]
	v_lshl_add_u64 v[54:55], v[36:37], 0, v[52:53]
	global_load_dword v92, v[38:39], off nt
	global_load_dword v91, v[40:41], off nt
	global_load_dword v52, v[42:43], off nt
	global_load_dword v53, v[44:45], off nt
	global_load_dword v89, v[46:47], off nt
	global_load_dword v90, v[48:49], off nt
	s_nop 0
	global_load_dword v50, v[50:51], off nt
	s_nop 0
	global_load_dword v51, v[54:55], off nt
	v_or_b32_e32 v48, 26, v2
	v_mov_b32_e32 v49, v3
	v_lshlrev_b64 v[48:49], 13, v[48:49]
	v_lshl_add_u64 v[54:55], v[36:37], 0, v[48:49]
	v_or_b32_e32 v48, 28, v2
	v_mov_b32_e32 v49, v3
	v_or_b32_e32 v38, 16, v2
	v_mov_b32_e32 v39, v3
	v_or_b32_e32 v44, 22, v2
	v_mov_b32_e32 v45, v3
	v_or_b32_e32 v46, 24, v2
	v_mov_b32_e32 v47, v3
	v_lshlrev_b64 v[48:49], 13, v[48:49]
	v_lshlrev_b64 v[38:39], 13, v[38:39]
	v_or_b32_e32 v40, 18, v2
	v_mov_b32_e32 v41, v3
	v_or_b32_e32 v42, 20, v2
	v_mov_b32_e32 v43, v3
	v_lshlrev_b64 v[44:45], 13, v[44:45]
	v_lshlrev_b64 v[46:47], 13, v[46:47]
	v_lshl_add_u64 v[80:81], v[36:37], 0, v[48:49]
	v_or_b32_e32 v48, 30, v2
	v_mov_b32_e32 v49, v3
	v_lshl_add_u64 v[38:39], v[36:37], 0, v[38:39]
	v_lshlrev_b64 v[40:41], 13, v[40:41]
	v_lshlrev_b64 v[42:43], 13, v[42:43]
	v_lshl_add_u64 v[44:45], v[36:37], 0, v[44:45]
	v_lshl_add_u64 v[46:47], v[36:37], 0, v[46:47]
	v_lshlrev_b64 v[48:49], 13, v[48:49]
	v_lshl_add_u64 v[40:41], v[36:37], 0, v[40:41]
	v_lshl_add_u64 v[42:43], v[36:37], 0, v[42:43]
	v_lshl_add_u64 v[82:83], v[36:37], 0, v[48:49]
	global_load_dword v87, v[38:39], off nt
	global_load_dword v88, v[40:41], off nt
	global_load_dword v48, v[42:43], off nt
	global_load_dword v49, v[44:45], off nt
	global_load_dword v85, v[46:47], off nt
	global_load_dword v86, v[54:55], off nt
	s_nop 0
	global_load_dword v46, v[80:81], off nt
	global_load_dword v47, v[82:83], off nt
	v_or_b32_e32 v44, 38, v2
	v_mov_b32_e32 v45, v3
	v_lshlrev_b64 v[44:45], 13, v[44:45]
	v_lshl_add_u64 v[54:55], v[36:37], 0, v[44:45]
	v_or_b32_e32 v44, 40, v2
	v_mov_b32_e32 v45, v3
	v_lshlrev_b64 v[44:45], 13, v[44:45]
	v_lshl_add_u64 v[80:81], v[36:37], 0, v[44:45]
	v_or_b32_e32 v44, 42, v2
	v_mov_b32_e32 v45, v3
	v_lshlrev_b64 v[44:45], 13, v[44:45]
	v_lshl_add_u64 v[94:95], v[36:37], 0, v[44:45]
	v_or_b32_e32 v44, 44, v2
	v_mov_b32_e32 v45, v3
	v_or_b32_e32 v38, 32, v2
	v_mov_b32_e32 v39, v3
	v_or_b32_e32 v40, 34, v2
	v_mov_b32_e32 v41, v3
	v_or_b32_e32 v42, 36, v2
	v_mov_b32_e32 v43, v3
	v_lshlrev_b64 v[44:45], 13, v[44:45]
	v_lshlrev_b64 v[38:39], 13, v[38:39]
	v_lshlrev_b64 v[40:41], 13, v[40:41]
	v_lshlrev_b64 v[42:43], 13, v[42:43]
	v_lshl_add_u64 v[96:97], v[36:37], 0, v[44:45]
	v_or_b32_e32 v44, 46, v2
	v_mov_b32_e32 v45, v3
	v_lshl_add_u64 v[38:39], v[36:37], 0, v[38:39]
	v_lshl_add_u64 v[40:41], v[36:37], 0, v[40:41]
	v_lshl_add_u64 v[42:43], v[36:37], 0, v[42:43]
	v_lshlrev_b64 v[44:45], 13, v[44:45]
	v_lshl_add_u64 v[98:99], v[36:37], 0, v[44:45]
	global_load_dword v83, v[38:39], off nt
	global_load_dword v84, v[40:41], off nt
	global_load_dword v44, v[42:43], off nt
	global_load_dword v45, v[54:55], off nt
	s_nop 0
	global_load_dword v81, v[80:81], off nt
	s_nop 0
	global_load_dword v82, v[94:95], off nt
	global_load_dword v42, v[96:97], off nt
	global_load_dword v43, v[98:99], off nt
	v_or_b32_e32 v38, 48, v2
	v_mov_b32_e32 v39, v3
	v_or_b32_e32 v40, 50, v2
	v_mov_b32_e32 v41, v3
	v_lshlrev_b64 v[38:39], 13, v[38:39]
	v_lshlrev_b64 v[40:41], 13, v[40:41]
	v_or_b32_e32 v54, 52, v2
	v_mov_b32_e32 v55, v3
	v_or_b32_e32 v94, 54, v2
	v_mov_b32_e32 v95, v3
	v_or_b32_e32 v96, 56, v2
	v_mov_b32_e32 v97, v3
	v_or_b32_e32 v98, 58, v2
	v_mov_b32_e32 v99, v3
	v_or_b32_e32 v100, 60, v2
	v_mov_b32_e32 v101, v3
	v_or_b32_e32 v102, 62, v2
	v_mov_b32_e32 v103, v3
	v_lshl_add_u64 v[38:39], v[36:37], 0, v[38:39]
	v_lshl_add_u64 v[40:41], v[36:37], 0, v[40:41]
	v_lshlrev_b64 v[54:55], 13, v[54:55]
	v_lshlrev_b64 v[94:95], 13, v[94:95]
	v_lshlrev_b64 v[96:97], 13, v[96:97]
	v_lshlrev_b64 v[98:99], 13, v[98:99]
	v_lshlrev_b64 v[100:101], 13, v[100:101]
	v_lshlrev_b64 v[102:103], 13, v[102:103]
	v_lshl_add_u64 v[54:55], v[36:37], 0, v[54:55]
	v_lshl_add_u64 v[94:95], v[36:37], 0, v[94:95]
	v_lshl_add_u64 v[96:97], v[36:37], 0, v[96:97]
	v_lshl_add_u64 v[98:99], v[36:37], 0, v[98:99]
	v_lshl_add_u64 v[100:101], v[36:37], 0, v[100:101]
	v_lshl_add_u64 v[102:103], v[36:37], 0, v[102:103]
	global_load_dword v79, v[38:39], off nt
	global_load_dword v80, v[40:41], off nt
	s_nop 0
	global_load_dword v40, v[54:55], off nt
	global_load_dword v41, v[94:95], off nt
	global_load_dword v33, v[96:97], off nt
	global_load_dword v35, v[98:99], off nt
	global_load_dword v36, v[100:101], off nt
	global_load_dword v37, v[102:103], off nt
	v_cndmask_b32_e64 v38, 0, 1, s[4:5]
	v_cmp_ne_u32_e64 s[0:1], 1, v38
	s_andn2_b64 vcc, exec, s[4:5]
	v_add_u32_e32 v38, s72, v56
	s_cbranch_vccnz .LBB0_127
	v_readlane_b32 s76, v252, 1
	v_readlane_b32 s90, v252, 15
	v_readlane_b32 s91, v252, 16
	v_mov_b32_e32 v39, v3
	v_add_u32_e32 v93, v57, v59
	v_lshl_add_u64 v[54:55], v[2:3], 2, s[90:91]
	v_lshl_add_u64 v[94:95], v[38:39], 2, s[90:91]
	global_load_dword v2, v[54:55], off nt
	global_load_dword v39, v[94:95], off offset:8 nt
	s_nop 0
	global_load_dword v54, v[94:95], off offset:16 nt
	global_load_dword v55, v[94:95], off offset:24 nt
	v_readlane_b32 s77, v252, 2
	v_readlane_b32 s78, v252, 3
	v_readlane_b32 s79, v252, 4
	v_readlane_b32 s80, v252, 5
	v_readlane_b32 s81, v252, 6
	v_readlane_b32 s82, v252, 7
	v_readlane_b32 s83, v252, 8
	v_readlane_b32 s84, v252, 9
	v_readlane_b32 s85, v252, 10
	v_readlane_b32 s86, v252, 11
	v_readlane_b32 s87, v252, 12
	v_readlane_b32 s88, v252, 13
	v_readlane_b32 s89, v252, 14
	s_waitcnt vmcnt(3)
	v_mul_f32_e32 v2, v92, v2
	s_waitcnt vmcnt(2)
	v_mul_f32_e32 v39, v91, v39
	ds_write_b32 v58, v2
	s_waitcnt vmcnt(0)
	v_pk_mul_f32 v[54:55], v[52:53], v[54:55]
	ds_write_b32 v93, v39
	s_cbranch_execnz .LBB0_21

.LBB0_21:
	v_add_u32_e32 v2, v57, v60
	s_and_b64 vcc, exec, s[0:1]
	ds_write2_b32 v2, v54, v55 offset1:66
	s_cbranch_vccnz .LBB0_128
	v_readlane_b32 s76, v252, 1
	v_mov_b32_e32 v39, v3
	v_readlane_b32 s90, v252, 15
	v_readlane_b32 s91, v252, 16
	s_waitcnt vmcnt(30)
	v_add_u32_e32 v91, v57, v61
	s_waitcnt vmcnt(28)
	v_lshl_add_u64 v[52:53], v[38:39], 2, s[90:91]
	global_load_dword v2, v[52:53], off offset:32 nt
	global_load_dword v39, v[52:53], off offset:40 nt
	global_load_dword v54, v[52:53], off offset:48 nt
	global_load_dword v55, v[52:53], off offset:56 nt
	v_readlane_b32 s77, v252, 2
	v_readlane_b32 s78, v252, 3
	v_readlane_b32 s79, v252, 4
	v_readlane_b32 s80, v252, 5
	v_readlane_b32 s81, v252, 6
	v_readlane_b32 s82, v252, 7
	v_readlane_b32 s83, v252, 8
	v_readlane_b32 s84, v252, 9
	v_readlane_b32 s85, v252, 10
	v_readlane_b32 s86, v252, 11
	v_readlane_b32 s87, v252, 12
	v_readlane_b32 s88, v252, 13
	v_readlane_b32 s89, v252, 14
	s_waitcnt vmcnt(3)
	v_mul_f32_e32 v2, v89, v2
	s_waitcnt vmcnt(2)
	v_mul_f32_e32 v39, v90, v39
	ds_write2_b32 v91, v2, v39 offset1:66
	s_waitcnt vmcnt(0)
	v_pk_mul_f32 v[52:53], v[50:51], v[54:55]
	s_cbranch_execnz .LBB0_24

.LBB0_24:
	v_add_u32_e32 v2, v57, v62
	s_and_b64 vcc, exec, s[0:1]
	s_waitcnt vmcnt(28)
	ds_write2_b32 v2, v52, v53 offset1:66
	s_cbranch_vccnz .LBB0_129
	v_readlane_b32 s76, v252, 1
	v_mov_b32_e32 v39, v3
	v_readlane_b32 s90, v252, 15
	v_readlane_b32 s91, v252, 16
	v_add_u32_e32 v54, v57, v63
	s_waitcnt vmcnt(24)
	v_lshl_add_u64 v[50:51], v[38:39], 2, s[90:91]
	global_load_dword v2, v[50:51], off offset:64 nt
	global_load_dword v39, v[50:51], off offset:72 nt
	global_load_dword v52, v[50:51], off offset:80 nt
	global_load_dword v53, v[50:51], off offset:88 nt
	v_readlane_b32 s77, v252, 2
	v_readlane_b32 s78, v252, 3
	v_readlane_b32 s79, v252, 4
	v_readlane_b32 s80, v252, 5
	v_readlane_b32 s81, v252, 6
	v_readlane_b32 s82, v252, 7
	v_readlane_b32 s83, v252, 8
	v_readlane_b32 s84, v252, 9
	v_readlane_b32 s85, v252, 10
	v_readlane_b32 s86, v252, 11
	v_readlane_b32 s87, v252, 12
	v_readlane_b32 s88, v252, 13
	v_readlane_b32 s89, v252, 14
	s_waitcnt vmcnt(3)
	v_mul_f32_e32 v2, v87, v2
	s_waitcnt vmcnt(2)
	v_mul_f32_e32 v39, v88, v39
	ds_write2_b32 v54, v2, v39 offset1:66
	s_waitcnt vmcnt(0)
	v_pk_mul_f32 v[50:51], v[48:49], v[52:53]
	s_cbranch_execnz .LBB0_27

.LBB0_27:
	v_add_u32_e32 v2, v57, v64
	s_and_b64 vcc, exec, s[0:1]
	s_waitcnt vmcnt(24)
	ds_write2_b32 v2, v50, v51 offset1:66
	s_cbranch_vccnz .LBB0_130
	v_readlane_b32 s76, v252, 1
	v_mov_b32_e32 v39, v3
	v_readlane_b32 s90, v252, 15
	v_readlane_b32 s91, v252, 16
	v_add_u32_e32 v52, v57, v65
	s_waitcnt vmcnt(20)
	v_lshl_add_u64 v[48:49], v[38:39], 2, s[90:91]
	global_load_dword v2, v[48:49], off offset:96 nt
	global_load_dword v39, v[48:49], off offset:104 nt
	global_load_dword v50, v[48:49], off offset:112 nt
	global_load_dword v51, v[48:49], off offset:120 nt
	v_readlane_b32 s77, v252, 2
	v_readlane_b32 s78, v252, 3
	v_readlane_b32 s79, v252, 4
	v_readlane_b32 s80, v252, 5
	v_readlane_b32 s81, v252, 6
	v_readlane_b32 s82, v252, 7
	v_readlane_b32 s83, v252, 8
	v_readlane_b32 s84, v252, 9
	v_readlane_b32 s85, v252, 10
	v_readlane_b32 s86, v252, 11
	v_readlane_b32 s87, v252, 12
	v_readlane_b32 s88, v252, 13
	v_readlane_b32 s89, v252, 14
	s_waitcnt vmcnt(3)
	v_mul_f32_e32 v2, v85, v2
	s_waitcnt vmcnt(2)
	v_mul_f32_e32 v39, v86, v39
	ds_write2_b32 v52, v2, v39 offset1:66
	s_waitcnt vmcnt(0)
	v_pk_mul_f32 v[48:49], v[46:47], v[50:51]
	s_cbranch_execnz .LBB0_30

.LBB0_30:
	v_add_u32_e32 v2, v57, v67
	s_and_b64 vcc, exec, s[0:1]
	s_waitcnt vmcnt(20)
	ds_write2_b32 v2, v48, v49 offset1:66
	s_cbranch_vccnz .LBB0_131
	v_readlane_b32 s76, v252, 1
	v_mov_b32_e32 v39, v3
	v_readlane_b32 s90, v252, 15
	v_readlane_b32 s91, v252, 16
	v_add_u32_e32 v50, v57, v69
	s_waitcnt vmcnt(16)
	v_lshl_add_u64 v[46:47], v[38:39], 2, s[90:91]
	global_load_dword v2, v[46:47], off offset:128 nt
	global_load_dword v39, v[46:47], off offset:136 nt
	global_load_dword v48, v[46:47], off offset:144 nt
	global_load_dword v49, v[46:47], off offset:152 nt
	v_readlane_b32 s77, v252, 2
	v_readlane_b32 s78, v252, 3
	v_readlane_b32 s79, v252, 4
	v_readlane_b32 s80, v252, 5
	v_readlane_b32 s81, v252, 6
	v_readlane_b32 s82, v252, 7
	v_readlane_b32 s83, v252, 8
	v_readlane_b32 s84, v252, 9
	v_readlane_b32 s85, v252, 10
	v_readlane_b32 s86, v252, 11
	v_readlane_b32 s87, v252, 12
	v_readlane_b32 s88, v252, 13
	v_readlane_b32 s89, v252, 14
	s_waitcnt vmcnt(3)
	v_mul_f32_e32 v2, v83, v2
	s_waitcnt vmcnt(2)
	v_mul_f32_e32 v39, v84, v39
	ds_write2_b32 v50, v2, v39 offset1:66
	s_waitcnt vmcnt(0)
	v_pk_mul_f32 v[46:47], v[44:45], v[48:49]
	s_cbranch_execnz .LBB0_33

.LBB0_33:
	v_add_u32_e32 v2, v57, v70
	s_and_b64 vcc, exec, s[0:1]
	s_waitcnt vmcnt(16)
	ds_write2_b32 v2, v46, v47 offset1:66
	s_cbranch_vccnz .LBB0_132
	v_readlane_b32 s76, v252, 1
	v_mov_b32_e32 v39, v3
	v_readlane_b32 s90, v252, 15
	v_readlane_b32 s91, v252, 16
	v_add_u32_e32 v48, v57, v71
	s_waitcnt vmcnt(12)
	v_lshl_add_u64 v[44:45], v[38:39], 2, s[90:91]
	global_load_dword v2, v[44:45], off offset:160 nt
	global_load_dword v39, v[44:45], off offset:168 nt
	global_load_dword v46, v[44:45], off offset:176 nt
	global_load_dword v47, v[44:45], off offset:184 nt
	v_readlane_b32 s77, v252, 2
	v_readlane_b32 s78, v252, 3
	v_readlane_b32 s79, v252, 4
	v_readlane_b32 s80, v252, 5
	v_readlane_b32 s81, v252, 6
	v_readlane_b32 s82, v252, 7
	v_readlane_b32 s83, v252, 8
	v_readlane_b32 s84, v252, 9
	v_readlane_b32 s85, v252, 10
	v_readlane_b32 s86, v252, 11
	v_readlane_b32 s87, v252, 12
	v_readlane_b32 s88, v252, 13
	v_readlane_b32 s89, v252, 14
	s_waitcnt vmcnt(3)
	v_mul_f32_e32 v2, v81, v2
	s_waitcnt vmcnt(2)
	v_mul_f32_e32 v39, v82, v39
	ds_write2_b32 v48, v2, v39 offset1:66
	s_waitcnt vmcnt(0)
	v_pk_mul_f32 v[44:45], v[42:43], v[46:47]
	s_cbranch_execnz .LBB0_36

.LBB0_36:
	v_add_u32_e32 v2, v57, v72
	s_and_b64 vcc, exec, s[0:1]
	s_waitcnt vmcnt(12)
	ds_write2_b32 v2, v44, v45 offset1:66
	s_cbranch_vccnz .LBB0_133
	v_readlane_b32 s76, v252, 1
	v_mov_b32_e32 v39, v3
	v_readlane_b32 s90, v252, 15
	v_readlane_b32 s91, v252, 16
	v_add_u32_e32 v46, v57, v73
	s_waitcnt vmcnt(8)
	v_lshl_add_u64 v[42:43], v[38:39], 2, s[90:91]
	global_load_dword v2, v[42:43], off offset:192 nt
	global_load_dword v39, v[42:43], off offset:200 nt
	global_load_dword v44, v[42:43], off offset:208 nt
	global_load_dword v45, v[42:43], off offset:216 nt
	v_readlane_b32 s77, v252, 2
	v_readlane_b32 s78, v252, 3
	v_readlane_b32 s79, v252, 4
	v_readlane_b32 s80, v252, 5
	v_readlane_b32 s81, v252, 6
	v_readlane_b32 s82, v252, 7
	v_readlane_b32 s83, v252, 8
	v_readlane_b32 s84, v252, 9
	v_readlane_b32 s85, v252, 10
	v_readlane_b32 s86, v252, 11
	v_readlane_b32 s87, v252, 12
	v_readlane_b32 s88, v252, 13
	v_readlane_b32 s89, v252, 14
	s_waitcnt vmcnt(3)
	v_mul_f32_e32 v2, v79, v2
	s_waitcnt vmcnt(2)
	v_mul_f32_e32 v39, v80, v39
	ds_write2_b32 v46, v2, v39 offset1:66
	s_waitcnt vmcnt(0)
	v_pk_mul_f32 v[42:43], v[40:41], v[44:45]
	s_cbranch_execnz .LBB0_39

.LBB0_39:
	v_add_u32_e32 v2, v57, v73
	s_waitcnt vmcnt(8)
	ds_write2_b32 v2, v42, v43 offset0:132 offset1:198
	s_and_b64 vcc, exec, s[0:1]
	v_add_u32_e32 v2, 0x400, v2
	s_cbranch_vccnz .LBB0_134
	v_readlane_b32 s76, v252, 1
	v_mov_b32_e32 v39, v3
	v_readlane_b32 s90, v252, 15
	v_readlane_b32 s91, v252, 16
	v_readlane_b32 s77, v252, 2
	s_nop 0
	v_lshl_add_u64 v[38:39], v[38:39], 2, s[90:91]
	global_load_dword v42, v[38:39], off offset:224 nt
	global_load_dword v43, v[38:39], off offset:232 nt
	global_load_dword v40, v[38:39], off offset:240 nt
	global_load_dword v41, v[38:39], off offset:248 nt
	v_readlane_b32 s78, v252, 3
	v_readlane_b32 s79, v252, 4
	v_readlane_b32 s80, v252, 5
	v_readlane_b32 s81, v252, 6
	v_readlane_b32 s82, v252, 7
	v_readlane_b32 s83, v252, 8
	v_readlane_b32 s84, v252, 9
	v_readlane_b32 s85, v252, 10
	v_readlane_b32 s86, v252, 11
	v_readlane_b32 s87, v252, 12
	v_readlane_b32 s88, v252, 13
	v_readlane_b32 s89, v252, 14
	s_waitcnt vmcnt(3)
	v_mul_f32_e32 v42, v33, v42
	s_waitcnt vmcnt(2)
	v_mul_f32_e32 v43, v35, v43
	ds_write2_b32 v2, v42, v43 offset0:8 offset1:74
	s_waitcnt vmcnt(0)
	v_pk_mul_f32 v[38:39], v[36:37], v[40:41]
	s_cbranch_execnz .LBB0_42

.LBB0_43:
	s_and_b64 vcc, exec, s[0:1]
	s_cbranch_vccz .LBB0_45
	s_and_b32 s0, s75, 0x7fc0
	s_addk_i32 s0, 0xb100
	s_add_i32 s1, s26, 0xfffffc00
	s_and_b32 s2, s1, 0x7e0
	v_or_b32_e32 v2, s0, v56
	s_lshl_b32 s72, s2, 2
	v_or_b32_e32 v40, 2, v2
	v_mov_b32_e32 v41, v3
	v_or_b32_e32 v42, 4, v2
	v_mov_b32_e32 v43, v3
	v_or_b32_e32 v44, 6, v2
	v_mov_b32_e32 v45, v3
	v_or_b32_e32 v46, 8, v2
	v_mov_b32_e32 v47, v3
	v_or_b32_e32 v48, 10, v2
	v_mov_b32_e32 v49, v3
	v_or_b32_e32 v50, 12, v2
	v_mov_b32_e32 v51, v3
	v_lshl_add_u64 v[36:37], v[6:7], 0, s[72:73]
	v_lshlrev_b64 v[38:39], 13, v[2:3]
	v_lshlrev_b64 v[40:41], 13, v[40:41]
	v_lshlrev_b64 v[42:43], 13, v[42:43]
	v_lshlrev_b64 v[44:45], 13, v[44:45]
	v_lshlrev_b64 v[46:47], 13, v[46:47]
	v_lshlrev_b64 v[48:49], 13, v[48:49]
	v_lshlrev_b64 v[50:51], 13, v[50:51]
	v_or_b32_e32 v52, 14, v2
	v_mov_b32_e32 v53, v3
	v_lshl_add_u64 v[38:39], v[36:37], 0, v[38:39]
	v_lshl_add_u64 v[40:41], v[36:37], 0, v[40:41]
	v_lshl_add_u64 v[42:43], v[36:37], 0, v[42:43]
	v_lshl_add_u64 v[44:45], v[36:37], 0, v[44:45]
	v_lshl_add_u64 v[46:47], v[36:37], 0, v[46:47]
	v_lshl_add_u64 v[48:49], v[36:37], 0, v[48:49]
	v_lshl_add_u64 v[50:51], v[36:37], 0, v[50:51]
	v_lshlrev_b64 v[52:53], 13, v[52:53]
	v_lshl_add_u64 v[52:53], v[36:37], 0, v[52:53]
	global_load_dword v33, v[38:39], off nt
	global_load_dword v35, v[40:41], off nt
	global_load_dword v54, v[42:43], off nt
	global_load_dword v55, v[44:45], off nt
	global_load_dword v79, v[46:47], off nt
	global_load_dword v80, v[48:49], off nt
	global_load_dword v81, v[50:51], off nt
	global_load_dword v82, v[52:53], off nt
	v_or_b32_e32 v38, 16, v2
	v_mov_b32_e32 v39, v3
	v_or_b32_e32 v40, 18, v2
	v_mov_b32_e32 v41, v3
	v_or_b32_e32 v42, 20, v2
	v_mov_b32_e32 v43, v3
	v_or_b32_e32 v44, 22, v2
	v_mov_b32_e32 v45, v3
	v_or_b32_e32 v46, 24, v2
	v_mov_b32_e32 v47, v3
	v_or_b32_e32 v48, 26, v2
	v_mov_b32_e32 v49, v3
	v_or_b32_e32 v50, 28, v2
	v_mov_b32_e32 v51, v3
	v_lshlrev_b64 v[38:39], 13, v[38:39]
	v_lshlrev_b64 v[40:41], 13, v[40:41]
	v_lshlrev_b64 v[42:43], 13, v[42:43]
	v_lshlrev_b64 v[44:45], 13, v[44:45]
	v_lshlrev_b64 v[46:47], 13, v[46:47]
	v_lshlrev_b64 v[48:49], 13, v[48:49]
	v_lshlrev_b64 v[50:51], 13, v[50:51]
	v_or_b32_e32 v52, 30, v2
	v_mov_b32_e32 v53, v3
	v_lshl_add_u64 v[38:39], v[36:37], 0, v[38:39]
	v_lshl_add_u64 v[40:41], v[36:37], 0, v[40:41]
	v_lshl_add_u64 v[42:43], v[36:37], 0, v[42:43]
	v_lshl_add_u64 v[44:45], v[36:37], 0, v[44:45]
	v_lshl_add_u64 v[46:47], v[36:37], 0, v[46:47]
	v_lshl_add_u64 v[48:49], v[36:37], 0, v[48:49]
	v_lshl_add_u64 v[50:51], v[36:37], 0, v[50:51]
	v_lshlrev_b64 v[52:53], 13, v[52:53]
	v_lshl_add_u64 v[52:53], v[36:37], 0, v[52:53]
	global_load_dword v83, v[38:39], off nt
	global_load_dword v84, v[40:41], off nt
	global_load_dword v85, v[42:43], off nt
	global_load_dword v86, v[44:45], off nt
	global_load_dword v87, v[46:47], off nt
	global_load_dword v88, v[48:49], off nt
	global_load_dword v89, v[50:51], off nt
	global_load_dword v90, v[52:53], off nt
	v_or_b32_e32 v38, 32, v2
	v_mov_b32_e32 v39, v3
	v_or_b32_e32 v40, 34, v2
	v_mov_b32_e32 v41, v3
	v_or_b32_e32 v42, 36, v2
	v_mov_b32_e32 v43, v3
	v_or_b32_e32 v44, 38, v2
	v_mov_b32_e32 v45, v3
	v_or_b32_e32 v46, 40, v2
	v_mov_b32_e32 v47, v3
	v_or_b32_e32 v48, 42, v2
	v_mov_b32_e32 v49, v3
	v_or_b32_e32 v50, 44, v2
	v_mov_b32_e32 v51, v3
	v_lshlrev_b64 v[38:39], 13, v[38:39]
	v_lshlrev_b64 v[40:41], 13, v[40:41]
	v_lshlrev_b64 v[42:43], 13, v[42:43]
	v_lshlrev_b64 v[44:45], 13, v[44:45]
	v_lshlrev_b64 v[46:47], 13, v[46:47]
	v_lshlrev_b64 v[48:49], 13, v[48:49]
	v_lshlrev_b64 v[50:51], 13, v[50:51]
	v_or_b32_e32 v52, 46, v2
	v_mov_b32_e32 v53, v3
	v_lshl_add_u64 v[38:39], v[36:37], 0, v[38:39]
	v_lshl_add_u64 v[40:41], v[36:37], 0, v[40:41]
	v_lshl_add_u64 v[42:43], v[36:37], 0, v[42:43]
	v_lshl_add_u64 v[44:45], v[36:37], 0, v[44:45]
	v_lshl_add_u64 v[46:47], v[36:37], 0, v[46:47]
	v_lshl_add_u64 v[48:49], v[36:37], 0, v[48:49]
	v_lshl_add_u64 v[50:51], v[36:37], 0, v[50:51]
	v_lshlrev_b64 v[52:53], 13, v[52:53]
	v_lshl_add_u64 v[52:53], v[36:37], 0, v[52:53]
	global_load_dword v91, v[38:39], off nt
	global_load_dword v92, v[40:41], off nt
	global_load_dword v93, v[42:43], off nt
	global_load_dword v94, v[44:45], off nt
	global_load_dword v95, v[46:47], off nt
	global_load_dword v96, v[48:49], off nt
	global_load_dword v97, v[50:51], off nt
	global_load_dword v98, v[52:53], off nt
	v_or_b32_e32 v38, 48, v2
	v_mov_b32_e32 v39, v3
	v_or_b32_e32 v40, 50, v2
	v_mov_b32_e32 v41, v3
	v_or_b32_e32 v42, 52, v2
	v_mov_b32_e32 v43, v3
	v_or_b32_e32 v44, 54, v2
	v_mov_b32_e32 v45, v3
	v_or_b32_e32 v46, 56, v2
	v_mov_b32_e32 v47, v3
	v_or_b32_e32 v48, 58, v2
	v_mov_b32_e32 v49, v3
	v_or_b32_e32 v50, 60, v2
	v_mov_b32_e32 v51, v3
	v_or_b32_e32 v2, 62, v2
	v_lshlrev_b64 v[38:39], 13, v[38:39]
	v_lshlrev_b64 v[40:41], 13, v[40:41]
	v_lshlrev_b64 v[42:43], 13, v[42:43]
	v_lshlrev_b64 v[44:45], 13, v[44:45]
	v_lshlrev_b64 v[46:47], 13, v[46:47]
	v_lshlrev_b64 v[48:49], 13, v[48:49]
	v_lshlrev_b64 v[50:51], 13, v[50:51]
	v_lshlrev_b64 v[52:53], 13, v[2:3]
	v_lshl_add_u64 v[38:39], v[36:37], 0, v[38:39]
	v_lshl_add_u64 v[40:41], v[36:37], 0, v[40:41]
	v_lshl_add_u64 v[42:43], v[36:37], 0, v[42:43]
	v_lshl_add_u64 v[44:45], v[36:37], 0, v[44:45]
	v_lshl_add_u64 v[46:47], v[36:37], 0, v[46:47]
	v_lshl_add_u64 v[48:49], v[36:37], 0, v[48:49]
	v_lshl_add_u64 v[50:51], v[36:37], 0, v[50:51]
	v_lshl_add_u64 v[36:37], v[36:37], 0, v[52:53]
	global_load_dword v2, v[38:39], off nt
	s_nop 0
	global_load_dword v38, v[40:41], off nt
	global_load_dword v39, v[42:43], off nt
	s_nop 0
	global_load_dword v40, v[44:45], off nt
	global_load_dword v41, v[46:47], off nt
	global_load_dword v42, v[48:49], off nt
	global_load_dword v43, v[50:51], off nt
	s_nop 0
	global_load_dword v36, v[36:37], off nt
	s_waitcnt vmcnt(30)
	ds_write2_b32 v58, v33, v35 offset1:66
	s_waitcnt vmcnt(28)
	ds_write2_b32 v58, v54, v55 offset0:132 offset1:198
	v_add_u32_e32 v33, 0x400, v58
	s_waitcnt vmcnt(26)
	ds_write2_b32 v33, v79, v80 offset0:8 offset1:74
	s_waitcnt vmcnt(24)
	ds_write2_b32 v33, v81, v82 offset0:140 offset1:206
	v_add_u32_e32 v33, 0x800, v58
	s_waitcnt vmcnt(22)
	ds_write2_b32 v33, v83, v84 offset0:16 offset1:82
	s_waitcnt vmcnt(20)
	ds_write2_b32 v33, v85, v86 offset0:148 offset1:214
	v_add_u32_e32 v33, 0xc00, v58
	s_waitcnt vmcnt(18)
	ds_write2_b32 v33, v87, v88 offset0:24 offset1:90
	s_waitcnt vmcnt(16)
	ds_write2_b32 v33, v89, v90 offset0:156 offset1:222
	v_add_u32_e32 v33, 0x1000, v58
	s_waitcnt vmcnt(14)
	ds_write2_b32 v33, v91, v92 offset0:32 offset1:98
	s_waitcnt vmcnt(12)
	ds_write2_b32 v33, v93, v94 offset0:164 offset1:230
	v_add_u32_e32 v33, 0x1400, v58
	s_waitcnt vmcnt(10)
	ds_write2_b32 v33, v95, v96 offset0:40 offset1:106
	s_waitcnt vmcnt(8)
	ds_write2_b32 v33, v97, v98 offset0:172 offset1:238
	v_add_u32_e32 v33, 0x1800, v58
	s_waitcnt vmcnt(6)
	ds_write2_b32 v33, v2, v38 offset0:48 offset1:114
	s_waitcnt vmcnt(4)
	ds_write2_b32 v33, v39, v40 offset0:180 offset1:246
	v_add_u32_e32 v2, 0x1c00, v58
	s_waitcnt vmcnt(2)
	ds_write2_b32 v2, v41, v42 offset0:56 offset1:122
	s_waitcnt vmcnt(0)
	ds_write2_b32 v2, v43, v36 offset0:188 offset1:254
	s_waitcnt lgkmcnt(0)
	ds_read2_b32 v[36:37], v75 offset1:33
	s_waitcnt lgkmcnt(0)
	v_cvt_pk_bf16_f32 v36, v36, v37
	ds_read2_b32 v[38:39], v75 offset0:66 offset1:99
	s_mov_b32 s1, s73
	v_or_b32_e32 v2, s2, v74
	s_waitcnt lgkmcnt(0)
	v_cvt_pk_bf16_f32 v37, v38, v39
	ds_read2_b32 v[38:39], v75 offset0:132 offset1:165
	v_lshl_add_u64 v[42:43], s[0:1], 1, v[8:9]
	v_lshlrev_b32_e32 v2, 14, v2
	s_waitcnt lgkmcnt(0)
	v_cvt_pk_bf16_f32 v38, v38, v39
	ds_read2_b32 v[40:41], v75 offset0:198 offset1:231
	s_waitcnt lgkmcnt(0)
	v_cvt_pk_bf16_f32 v39, v40, v41
	v_lshl_add_u64 v[44:45], v[42:43], 0, v[2:3]
	ds_read2_b32 v[40:41], v75 offset0:8 offset1:41
	global_store_dwordx4 v[44:45], v[36:39], off
	v_or_b32_e32 v2, s2, v76
	v_lshlrev_b32_e32 v2, 14, v2
	s_waitcnt lgkmcnt(0)
	v_cvt_pk_bf16_f32 v36, v40, v41
	ds_read2_b32 v[38:39], v75 offset0:74 offset1:107
	s_waitcnt lgkmcnt(0)
	v_cvt_pk_bf16_f32 v37, v38, v39
	ds_read2_b32 v[38:39], v75 offset0:140 offset1:173
	s_waitcnt lgkmcnt(0)
	v_cvt_pk_bf16_f32 v38, v38, v39
	ds_read2_b32 v[40:41], v75 offset0:206 offset1:239
	s_waitcnt lgkmcnt(0)
	v_cvt_pk_bf16_f32 v39, v40, v41
	v_lshl_add_u64 v[44:45], v[42:43], 0, v[2:3]
	ds_read2_b32 v[40:41], v75 offset0:16 offset1:49
	global_store_dwordx4 v[44:45], v[36:39], off
	v_or_b32_e32 v2, s2, v77
	v_lshlrev_b32_e32 v2, 14, v2
	s_waitcnt lgkmcnt(0)
	v_cvt_pk_bf16_f32 v36, v40, v41
	ds_read2_b32 v[38:39], v75 offset0:82 offset1:115
	s_waitcnt lgkmcnt(0)
	v_cvt_pk_bf16_f32 v37, v38, v39
	ds_read2_b32 v[38:39], v75 offset0:148 offset1:181
	s_waitcnt lgkmcnt(0)
	v_cvt_pk_bf16_f32 v38, v38, v39
	ds_read2_b32 v[40:41], v75 offset0:214 offset1:247
	s_waitcnt lgkmcnt(0)
	v_cvt_pk_bf16_f32 v39, v40, v41
	v_lshl_add_u64 v[44:45], v[42:43], 0, v[2:3]
	ds_read2_b32 v[40:41], v75 offset0:24 offset1:57
	global_store_dwordx4 v[44:45], v[36:39], off
	v_or_b32_e32 v2, s2, v78
	v_lshlrev_b32_e32 v2, 14, v2
	s_waitcnt lgkmcnt(0)
	v_cvt_pk_bf16_f32 v36, v40, v41
	ds_read2_b32 v[38:39], v75 offset0:90 offset1:123
	s_waitcnt lgkmcnt(0)
	v_cvt_pk_bf16_f32 v37, v38, v39
	ds_read2_b32 v[38:39], v75 offset0:156 offset1:189
	s_waitcnt lgkmcnt(0)
	v_cvt_pk_bf16_f32 v38, v38, v39
	ds_read2_b32 v[40:41], v75 offset0:222 offset1:255
	s_waitcnt lgkmcnt(0)
	v_cvt_pk_bf16_f32 v39, v40, v41
	v_lshl_add_u64 v[40:41], v[42:43], 0, v[2:3]
	global_store_dwordx4 v[40:41], v[36:39], off
	s_waitcnt lgkmcnt(0)

.LBB0_46:
	s_andn2_b64 vcc, exec, s[0:1]
	s_cbranch_vccnz .LBB0_72
	s_add_i32 s0, s75, 0xffffd100
	s_lshr_b32 s0, s0, 2
	s_add_i32 s1, s26, 0xfffffc00
	s_and_b32 s3, s0, 0x3fffffc0
	s_and_b32 s2, s1, 0x1fe0
	v_or_b32_e32 v2, s3, v56
	s_lshl_b32 s72, s2, 2
	v_or_b32_e32 v48, 10, v2
	v_mov_b32_e32 v49, v3
	v_or_b32_e32 v50, 12, v2
	v_mov_b32_e32 v51, v3
	v_lshl_add_u64 v[36:37], v[10:11], 0, s[72:73]
	v_lshlrev_b64 v[38:39], 15, v[2:3]
	v_or_b32_e32 v40, 2, v2
	v_mov_b32_e32 v41, v3
	v_or_b32_e32 v42, 4, v2
	v_mov_b32_e32 v43, v3
	v_or_b32_e32 v44, 6, v2
	v_mov_b32_e32 v45, v3
	v_or_b32_e32 v46, 8, v2
	v_mov_b32_e32 v47, v3
	v_lshlrev_b64 v[48:49], 15, v[48:49]
	v_lshlrev_b64 v[50:51], 15, v[50:51]
	v_or_b32_e32 v52, 14, v2
	v_mov_b32_e32 v53, v3
	v_lshl_add_u64 v[38:39], v[36:37], 0, v[38:39]
	v_lshlrev_b64 v[40:41], 15, v[40:41]
	v_lshlrev_b64 v[42:43], 15, v[42:43]
	v_lshlrev_b64 v[44:45], 15, v[44:45]
	v_lshlrev_b64 v[46:47], 15, v[46:47]
	v_lshl_add_u64 v[48:49], v[36:37], 0, v[48:49]
	v_lshl_add_u64 v[50:51], v[36:37], 0, v[50:51]
	v_lshlrev_b64 v[52:53], 15, v[52:53]
	v_lshl_add_u64 v[40:41], v[36:37], 0, v[40:41]
	v_lshl_add_u64 v[42:43], v[36:37], 0, v[42:43]
	v_lshl_add_u64 v[44:45], v[36:37], 0, v[44:45]
	v_lshl_add_u64 v[46:47], v[36:37], 0, v[46:47]
	v_lshl_add_u64 v[54:55], v[36:37], 0, v[52:53]
	global_load_dword v92, v[38:39], off nt
	global_load_dword v91, v[40:41], off nt
	global_load_dword v52, v[42:43], off nt
	global_load_dword v53, v[44:45], off nt
	global_load_dword v89, v[46:47], off nt
	global_load_dword v90, v[48:49], off nt
	s_nop 0
	global_load_dword v50, v[50:51], off nt
	s_nop 0
	global_load_dword v51, v[54:55], off nt
	v_or_b32_e32 v48, 26, v2
	v_mov_b32_e32 v49, v3
	v_lshlrev_b64 v[48:49], 15, v[48:49]
	v_lshl_add_u64 v[54:55], v[36:37], 0, v[48:49]
	v_or_b32_e32 v48, 28, v2
	v_mov_b32_e32 v49, v3
	v_or_b32_e32 v38, 16, v2
	v_mov_b32_e32 v39, v3
	v_or_b32_e32 v44, 22, v2
	v_mov_b32_e32 v45, v3
	v_or_b32_e32 v46, 24, v2
	v_mov_b32_e32 v47, v3
	v_lshlrev_b64 v[48:49], 15, v[48:49]
	v_lshlrev_b64 v[38:39], 15, v[38:39]
	v_or_b32_e32 v40, 18, v2
	v_mov_b32_e32 v41, v3
	v_or_b32_e32 v42, 20, v2
	v_mov_b32_e32 v43, v3
	v_lshlrev_b64 v[44:45], 15, v[44:45]
	v_lshlrev_b64 v[46:47], 15, v[46:47]
	v_lshl_add_u64 v[80:81], v[36:37], 0, v[48:49]
	v_or_b32_e32 v48, 30, v2
	v_mov_b32_e32 v49, v3
	v_lshl_add_u64 v[38:39], v[36:37], 0, v[38:39]
	v_lshlrev_b64 v[40:41], 15, v[40:41]
	v_lshlrev_b64 v[42:43], 15, v[42:43]
	v_lshl_add_u64 v[44:45], v[36:37], 0, v[44:45]
	v_lshl_add_u64 v[46:47], v[36:37], 0, v[46:47]
	v_lshlrev_b64 v[48:49], 15, v[48:49]
	v_lshl_add_u64 v[40:41], v[36:37], 0, v[40:41]
	v_lshl_add_u64 v[42:43], v[36:37], 0, v[42:43]
	v_lshl_add_u64 v[82:83], v[36:37], 0, v[48:49]
	global_load_dword v87, v[38:39], off nt
	global_load_dword v88, v[40:41], off nt
	global_load_dword v48, v[42:43], off nt
	global_load_dword v49, v[44:45], off nt
	global_load_dword v85, v[46:47], off nt
	global_load_dword v86, v[54:55], off nt
	s_nop 0
	global_load_dword v46, v[80:81], off nt
	global_load_dword v47, v[82:83], off nt
	v_or_b32_e32 v44, 38, v2
	v_mov_b32_e32 v45, v3
	v_lshlrev_b64 v[44:45], 15, v[44:45]
	v_lshl_add_u64 v[54:55], v[36:37], 0, v[44:45]
	v_or_b32_e32 v44, 40, v2
	v_mov_b32_e32 v45, v3
	v_lshlrev_b64 v[44:45], 15, v[44:45]
	v_lshl_add_u64 v[80:81], v[36:37], 0, v[44:45]
	v_or_b32_e32 v44, 42, v2
	v_mov_b32_e32 v45, v3
	v_lshlrev_b64 v[44:45], 15, v[44:45]
	v_lshl_add_u64 v[94:95], v[36:37], 0, v[44:45]
	v_or_b32_e32 v44, 44, v2
	v_mov_b32_e32 v45, v3
	v_or_b32_e32 v38, 32, v2
	v_mov_b32_e32 v39, v3
	v_or_b32_e32 v40, 34, v2
	v_mov_b32_e32 v41, v3
	v_or_b32_e32 v42, 36, v2
	v_mov_b32_e32 v43, v3
	v_lshlrev_b64 v[44:45], 15, v[44:45]
	v_lshlrev_b64 v[38:39], 15, v[38:39]
	v_lshlrev_b64 v[40:41], 15, v[40:41]
	v_lshlrev_b64 v[42:43], 15, v[42:43]
	v_lshl_add_u64 v[96:97], v[36:37], 0, v[44:45]
	v_or_b32_e32 v44, 46, v2
	v_mov_b32_e32 v45, v3
	v_lshl_add_u64 v[38:39], v[36:37], 0, v[38:39]
	v_lshl_add_u64 v[40:41], v[36:37], 0, v[40:41]
	v_lshl_add_u64 v[42:43], v[36:37], 0, v[42:43]
	v_lshlrev_b64 v[44:45], 15, v[44:45]
	v_lshl_add_u64 v[98:99], v[36:37], 0, v[44:45]
	global_load_dword v83, v[38:39], off nt
	global_load_dword v84, v[40:41], off nt
	global_load_dword v44, v[42:43], off nt
	global_load_dword v45, v[54:55], off nt
	s_nop 0
	global_load_dword v81, v[80:81], off nt
	s_nop 0
	global_load_dword v82, v[94:95], off nt
	global_load_dword v42, v[96:97], off nt
	global_load_dword v43, v[98:99], off nt
	v_or_b32_e32 v38, 48, v2
	v_mov_b32_e32 v39, v3
	v_or_b32_e32 v40, 50, v2
	v_mov_b32_e32 v41, v3
	v_lshlrev_b64 v[38:39], 15, v[38:39]
	v_lshlrev_b64 v[40:41], 15, v[40:41]
	v_or_b32_e32 v54, 52, v2
	v_mov_b32_e32 v55, v3
	v_or_b32_e32 v94, 54, v2
	v_mov_b32_e32 v95, v3
	v_or_b32_e32 v96, 56, v2
	v_mov_b32_e32 v97, v3
	v_or_b32_e32 v98, 58, v2
	v_mov_b32_e32 v99, v3
	v_or_b32_e32 v100, 60, v2
	v_mov_b32_e32 v101, v3
	v_or_b32_e32 v102, 62, v2
	v_mov_b32_e32 v103, v3
	v_lshl_add_u64 v[38:39], v[36:37], 0, v[38:39]
	v_lshl_add_u64 v[40:41], v[36:37], 0, v[40:41]
	v_lshlrev_b64 v[54:55], 15, v[54:55]
	v_lshlrev_b64 v[94:95], 15, v[94:95]
	v_lshlrev_b64 v[96:97], 15, v[96:97]
	v_lshlrev_b64 v[98:99], 15, v[98:99]
	v_lshlrev_b64 v[100:101], 15, v[100:101]
	v_lshlrev_b64 v[102:103], 15, v[102:103]
	v_lshl_add_u64 v[54:55], v[36:37], 0, v[54:55]
	v_lshl_add_u64 v[94:95], v[36:37], 0, v[94:95]
	v_lshl_add_u64 v[96:97], v[36:37], 0, v[96:97]
	v_lshl_add_u64 v[98:99], v[36:37], 0, v[98:99]
	v_lshl_add_u64 v[100:101], v[36:37], 0, v[100:101]
	v_lshl_add_u64 v[102:103], v[36:37], 0, v[102:103]
	global_load_dword v79, v[38:39], off nt
	global_load_dword v80, v[40:41], off nt
	s_nop 0
	global_load_dword v40, v[54:55], off nt
	global_load_dword v41, v[94:95], off nt
	global_load_dword v33, v[96:97], off nt
	global_load_dword v35, v[98:99], off nt
	global_load_dword v36, v[100:101], off nt
	global_load_dword v37, v[102:103], off nt
	v_cndmask_b32_e64 v38, 0, 1, s[24:25]
	v_cmp_ne_u32_e64 s[0:1], 1, v38
	s_andn2_b64 vcc, exec, s[24:25]
	v_add_u32_e32 v38, s3, v56
	s_cbranch_vccnz .LBB0_119
	v_lshlrev_b32_e32 v2, 2, v2
	v_mov_b32_e32 v39, v3
	v_lshl_add_u64 v[54:55], v[38:39], 2, s[22:23]
	global_load_dword v2, v2, s[22:23]
	s_nop 0
	global_load_dword v39, v[54:55], off offset:8 nt
	global_load_dword v94, v[54:55], off offset:16 nt
	global_load_dword v95, v[54:55], off offset:24 nt
	v_add_u32_e32 v93, v57, v59
	s_waitcnt vmcnt(3)
	v_mul_f32_e32 v2, v92, v2
	s_waitcnt vmcnt(2)
	v_mul_f32_e32 v39, v91, v39
	ds_write_b32 v58, v2
	s_waitcnt vmcnt(0)
	v_pk_mul_f32 v[54:55], v[52:53], v[94:95]
	ds_write_b32 v93, v39
	s_cbranch_execnz .LBB0_50

.LBB0_50:
	v_add_u32_e32 v2, v57, v60
	s_and_b64 vcc, exec, s[0:1]
	ds_write2_b32 v2, v54, v55 offset1:66
	s_cbranch_vccnz .LBB0_120
	v_mov_b32_e32 v39, v3
	s_waitcnt vmcnt(28)
	v_lshl_add_u64 v[52:53], v[38:39], 2, s[22:23]
	global_load_dword v2, v[52:53], off offset:32 nt
	global_load_dword v39, v[52:53], off offset:40 nt
	global_load_dword v54, v[52:53], off offset:48 nt
	global_load_dword v55, v[52:53], off offset:56 nt
	v_add_u32_e32 v91, v57, v61
	s_waitcnt vmcnt(3)
	v_mul_f32_e32 v2, v89, v2
	s_waitcnt vmcnt(2)
	v_mul_f32_e32 v39, v90, v39
	ds_write2_b32 v91, v2, v39 offset1:66
	s_waitcnt vmcnt(0)
	v_pk_mul_f32 v[52:53], v[50:51], v[54:55]
	s_cbranch_execnz .LBB0_53

.LBB0_53:
	v_add_u32_e32 v2, v57, v62
	s_and_b64 vcc, exec, s[0:1]
	s_waitcnt vmcnt(28)
	ds_write2_b32 v2, v52, v53 offset1:66
	s_cbranch_vccnz .LBB0_121
	v_mov_b32_e32 v39, v3
	s_waitcnt vmcnt(24)
	v_lshl_add_u64 v[50:51], v[38:39], 2, s[22:23]
	global_load_dword v2, v[50:51], off offset:64 nt
	global_load_dword v39, v[50:51], off offset:72 nt
	global_load_dword v52, v[50:51], off offset:80 nt
	global_load_dword v53, v[50:51], off offset:88 nt
	v_add_u32_e32 v54, v57, v63
	s_waitcnt vmcnt(3)
	v_mul_f32_e32 v2, v87, v2
	s_waitcnt vmcnt(2)
	v_mul_f32_e32 v39, v88, v39
	ds_write2_b32 v54, v2, v39 offset1:66
	s_waitcnt vmcnt(0)
	v_pk_mul_f32 v[50:51], v[48:49], v[52:53]
	s_cbranch_execnz .LBB0_56

.LBB0_56:
	v_add_u32_e32 v2, v57, v64
	s_and_b64 vcc, exec, s[0:1]
	s_waitcnt vmcnt(24)
	ds_write2_b32 v2, v50, v51 offset1:66
	s_cbranch_vccnz .LBB0_122
	v_mov_b32_e32 v39, v3
	s_waitcnt vmcnt(20)
	v_lshl_add_u64 v[48:49], v[38:39], 2, s[22:23]
	global_load_dword v2, v[48:49], off offset:96 nt
	global_load_dword v39, v[48:49], off offset:104 nt
	global_load_dword v50, v[48:49], off offset:112 nt
	global_load_dword v51, v[48:49], off offset:120 nt
	v_add_u32_e32 v52, v57, v65
	s_waitcnt vmcnt(3)
	v_mul_f32_e32 v2, v85, v2
	s_waitcnt vmcnt(2)
	v_mul_f32_e32 v39, v86, v39
	ds_write2_b32 v52, v2, v39 offset1:66
	s_waitcnt vmcnt(0)
	v_pk_mul_f32 v[48:49], v[46:47], v[50:51]
	s_cbranch_execnz .LBB0_59

.LBB0_59:
	v_add_u32_e32 v2, v57, v67
	s_and_b64 vcc, exec, s[0:1]
	s_waitcnt vmcnt(20)
	ds_write2_b32 v2, v48, v49 offset1:66
	s_cbranch_vccnz .LBB0_123
	v_mov_b32_e32 v39, v3
	s_waitcnt vmcnt(16)
	v_lshl_add_u64 v[46:47], v[38:39], 2, s[22:23]
	global_load_dword v2, v[46:47], off offset:128 nt
	global_load_dword v39, v[46:47], off offset:136 nt
	global_load_dword v48, v[46:47], off offset:144 nt
	global_load_dword v49, v[46:47], off offset:152 nt
	v_add_u32_e32 v50, v57, v69
	s_waitcnt vmcnt(3)
	v_mul_f32_e32 v2, v83, v2
	s_waitcnt vmcnt(2)
	v_mul_f32_e32 v39, v84, v39
	ds_write2_b32 v50, v2, v39 offset1:66
	s_waitcnt vmcnt(0)
	v_pk_mul_f32 v[46:47], v[44:45], v[48:49]
	s_cbranch_execnz .LBB0_62

.LBB0_62:
	v_add_u32_e32 v2, v57, v70
	s_and_b64 vcc, exec, s[0:1]
	s_waitcnt vmcnt(16)
	ds_write2_b32 v2, v46, v47 offset1:66
	s_cbranch_vccnz .LBB0_124
	v_mov_b32_e32 v39, v3
	s_waitcnt vmcnt(12)
	v_lshl_add_u64 v[44:45], v[38:39], 2, s[22:23]
	global_load_dword v2, v[44:45], off offset:160 nt
	global_load_dword v39, v[44:45], off offset:168 nt
	global_load_dword v46, v[44:45], off offset:176 nt
	global_load_dword v47, v[44:45], off offset:184 nt
	v_add_u32_e32 v48, v57, v71
	s_waitcnt vmcnt(3)
	v_mul_f32_e32 v2, v81, v2
	s_waitcnt vmcnt(2)
	v_mul_f32_e32 v39, v82, v39
	ds_write2_b32 v48, v2, v39 offset1:66
	s_waitcnt vmcnt(0)
	v_pk_mul_f32 v[44:45], v[42:43], v[46:47]
	s_cbranch_execnz .LBB0_65

.LBB0_65:
	v_add_u32_e32 v2, v57, v72
	s_and_b64 vcc, exec, s[0:1]
	s_waitcnt vmcnt(12)
	ds_write2_b32 v2, v44, v45 offset1:66
	s_cbranch_vccnz .LBB0_125
	v_mov_b32_e32 v39, v3
	s_waitcnt vmcnt(8)
	v_lshl_add_u64 v[42:43], v[38:39], 2, s[22:23]
	global_load_dword v2, v[42:43], off offset:192 nt
	global_load_dword v39, v[42:43], off offset:200 nt
	global_load_dword v44, v[42:43], off offset:208 nt
	global_load_dword v45, v[42:43], off offset:216 nt
	v_add_u32_e32 v46, v57, v73
	s_waitcnt vmcnt(3)
	v_mul_f32_e32 v2, v79, v2
	s_waitcnt vmcnt(2)
	v_mul_f32_e32 v39, v80, v39
	ds_write2_b32 v46, v2, v39 offset1:66
	s_waitcnt vmcnt(0)
	v_pk_mul_f32 v[42:43], v[40:41], v[44:45]
	s_cbranch_execnz .LBB0_68

.LBB0_68:
	v_add_u32_e32 v2, v57, v73
	s_waitcnt vmcnt(8)
	ds_write2_b32 v2, v42, v43 offset0:132 offset1:198
	s_and_b64 vcc, exec, s[0:1]
	v_add_u32_e32 v2, 0x400, v2
	s_cbranch_vccnz .LBB0_126
	v_mov_b32_e32 v39, v3
	v_lshl_add_u64 v[38:39], v[38:39], 2, s[22:23]
	global_load_dword v42, v[38:39], off offset:224 nt
	global_load_dword v43, v[38:39], off offset:232 nt
	global_load_dword v40, v[38:39], off offset:240 nt
	global_load_dword v41, v[38:39], off offset:248 nt
	s_waitcnt vmcnt(3)
	v_mul_f32_e32 v42, v33, v42
	s_waitcnt vmcnt(2)
	v_mul_f32_e32 v43, v35, v43
	ds_write2_b32 v2, v42, v43 offset0:8 offset1:74
	s_waitcnt vmcnt(0)
	v_pk_mul_f32 v[38:39], v[36:37], v[40:41]
	s_cbranch_execnz .LBB0_71

.LBB0_73:
	s_andn2_b64 vcc, exec, s[0:1]
	s_cbranch_vccnz .LBB0_75
	s_add_i32 s1, s75, 0xffffe100
	s_lshr_b32 s1, s1, 1
	s_add_i32 s0, s26, 0xfffffc00
	s_and_b32 s1, s1, 0x7fffffc0
	s_and_b32 s0, s0, 0xfe0
	v_or_b32_e32 v2, s1, v56
	s_lshl_b32 s72, s0, 2
	v_or_b32_e32 v40, 2, v2
	v_mov_b32_e32 v41, v3
	v_or_b32_e32 v42, 4, v2
	v_mov_b32_e32 v43, v3
	v_or_b32_e32 v44, 6, v2
	v_mov_b32_e32 v45, v3
	v_or_b32_e32 v46, 8, v2
	v_mov_b32_e32 v47, v3
	v_or_b32_e32 v48, 10, v2
	v_mov_b32_e32 v49, v3
	v_or_b32_e32 v50, 12, v2
	v_mov_b32_e32 v51, v3
	v_lshl_add_u64 v[36:37], v[14:15], 0, s[72:73]
	v_lshlrev_b64 v[38:39], 14, v[2:3]
	v_lshlrev_b64 v[40:41], 14, v[40:41]
	v_lshlrev_b64 v[42:43], 14, v[42:43]
	v_lshlrev_b64 v[44:45], 14, v[44:45]
	v_lshlrev_b64 v[46:47], 14, v[46:47]
	v_lshlrev_b64 v[48:49], 14, v[48:49]
	v_lshlrev_b64 v[50:51], 14, v[50:51]
	v_or_b32_e32 v52, 14, v2
	v_mov_b32_e32 v53, v3
	v_lshl_add_u64 v[38:39], v[36:37], 0, v[38:39]
	v_lshl_add_u64 v[40:41], v[36:37], 0, v[40:41]
	v_lshl_add_u64 v[42:43], v[36:37], 0, v[42:43]
	v_lshl_add_u64 v[44:45], v[36:37], 0, v[44:45]
	v_lshl_add_u64 v[46:47], v[36:37], 0, v[46:47]
	v_lshl_add_u64 v[48:49], v[36:37], 0, v[48:49]
	v_lshl_add_u64 v[50:51], v[36:37], 0, v[50:51]
	v_lshlrev_b64 v[52:53], 14, v[52:53]
	v_lshl_add_u64 v[52:53], v[36:37], 0, v[52:53]
	global_load_dword v33, v[38:39], off nt
	global_load_dword v35, v[40:41], off nt
	global_load_dword v54, v[42:43], off nt
	global_load_dword v55, v[44:45], off nt
	global_load_dword v79, v[46:47], off nt
	global_load_dword v80, v[48:49], off nt
	global_load_dword v81, v[50:51], off nt
	global_load_dword v82, v[52:53], off nt
	v_or_b32_e32 v38, 16, v2
	v_mov_b32_e32 v39, v3
	v_or_b32_e32 v40, 18, v2
	v_mov_b32_e32 v41, v3
	v_or_b32_e32 v42, 20, v2
	v_mov_b32_e32 v43, v3
	v_or_b32_e32 v44, 22, v2
	v_mov_b32_e32 v45, v3
	v_or_b32_e32 v46, 24, v2
	v_mov_b32_e32 v47, v3
	v_or_b32_e32 v48, 26, v2
	v_mov_b32_e32 v49, v3
	v_or_b32_e32 v50, 28, v2
	v_mov_b32_e32 v51, v3
	v_lshlrev_b64 v[38:39], 14, v[38:39]
	v_lshlrev_b64 v[40:41], 14, v[40:41]
	v_lshlrev_b64 v[42:43], 14, v[42:43]
	v_lshlrev_b64 v[44:45], 14, v[44:45]
	v_lshlrev_b64 v[46:47], 14, v[46:47]
	v_lshlrev_b64 v[48:49], 14, v[48:49]
	v_lshlrev_b64 v[50:51], 14, v[50:51]
	v_or_b32_e32 v52, 30, v2
	v_mov_b32_e32 v53, v3
	v_lshl_add_u64 v[38:39], v[36:37], 0, v[38:39]
	v_lshl_add_u64 v[40:41], v[36:37], 0, v[40:41]
	v_lshl_add_u64 v[42:43], v[36:37], 0, v[42:43]
	v_lshl_add_u64 v[44:45], v[36:37], 0, v[44:45]
	v_lshl_add_u64 v[46:47], v[36:37], 0, v[46:47]
	v_lshl_add_u64 v[48:49], v[36:37], 0, v[48:49]
	v_lshl_add_u64 v[50:51], v[36:37], 0, v[50:51]
	v_lshlrev_b64 v[52:53], 14, v[52:53]
	v_lshl_add_u64 v[52:53], v[36:37], 0, v[52:53]
	global_load_dword v83, v[38:39], off nt
	global_load_dword v84, v[40:41], off nt
	global_load_dword v85, v[42:43], off nt
	global_load_dword v86, v[44:45], off nt
	global_load_dword v87, v[46:47], off nt
	global_load_dword v88, v[48:49], off nt
	global_load_dword v89, v[50:51], off nt
	global_load_dword v90, v[52:53], off nt
	v_or_b32_e32 v38, 32, v2
	v_mov_b32_e32 v39, v3
	v_or_b32_e32 v40, 34, v2
	v_mov_b32_e32 v41, v3
	v_or_b32_e32 v42, 36, v2
	v_mov_b32_e32 v43, v3
	v_or_b32_e32 v44, 38, v2
	v_mov_b32_e32 v45, v3
	v_or_b32_e32 v46, 40, v2
	v_mov_b32_e32 v47, v3
	v_or_b32_e32 v48, 42, v2
	v_mov_b32_e32 v49, v3
	v_or_b32_e32 v50, 44, v2
	v_mov_b32_e32 v51, v3
	v_lshlrev_b64 v[38:39], 14, v[38:39]
	v_lshlrev_b64 v[40:41], 14, v[40:41]
	v_lshlrev_b64 v[42:43], 14, v[42:43]
	v_lshlrev_b64 v[44:45], 14, v[44:45]
	v_lshlrev_b64 v[46:47], 14, v[46:47]
	v_lshlrev_b64 v[48:49], 14, v[48:49]
	v_lshlrev_b64 v[50:51], 14, v[50:51]
	v_or_b32_e32 v52, 46, v2
	v_mov_b32_e32 v53, v3
	v_lshl_add_u64 v[38:39], v[36:37], 0, v[38:39]
	v_lshl_add_u64 v[40:41], v[36:37], 0, v[40:41]
	v_lshl_add_u64 v[42:43], v[36:37], 0, v[42:43]
	v_lshl_add_u64 v[44:45], v[36:37], 0, v[44:45]
	v_lshl_add_u64 v[46:47], v[36:37], 0, v[46:47]
	v_lshl_add_u64 v[48:49], v[36:37], 0, v[48:49]
	v_lshl_add_u64 v[50:51], v[36:37], 0, v[50:51]
	v_lshlrev_b64 v[52:53], 14, v[52:53]
	v_lshl_add_u64 v[52:53], v[36:37], 0, v[52:53]
	global_load_dword v91, v[38:39], off nt
	global_load_dword v92, v[40:41], off nt
	global_load_dword v93, v[42:43], off nt
	global_load_dword v94, v[44:45], off nt
	global_load_dword v95, v[46:47], off nt
	global_load_dword v96, v[48:49], off nt
	global_load_dword v97, v[50:51], off nt
	global_load_dword v98, v[52:53], off nt
	v_or_b32_e32 v38, 48, v2
	v_mov_b32_e32 v39, v3
	v_or_b32_e32 v40, 50, v2
	v_mov_b32_e32 v41, v3
	v_or_b32_e32 v42, 52, v2
	v_mov_b32_e32 v43, v3
	v_or_b32_e32 v44, 54, v2
	v_mov_b32_e32 v45, v3
	v_or_b32_e32 v46, 56, v2
	v_mov_b32_e32 v47, v3
	v_or_b32_e32 v48, 58, v2
	v_mov_b32_e32 v49, v3
	v_or_b32_e32 v50, 60, v2
	v_mov_b32_e32 v51, v3
	v_or_b32_e32 v2, 62, v2
	v_lshlrev_b64 v[38:39], 14, v[38:39]
	v_lshlrev_b64 v[40:41], 14, v[40:41]
	v_lshlrev_b64 v[42:43], 14, v[42:43]
	v_lshlrev_b64 v[44:45], 14, v[44:45]
	v_lshlrev_b64 v[46:47], 14, v[46:47]
	v_lshlrev_b64 v[48:49], 14, v[48:49]
	v_lshlrev_b64 v[50:51], 14, v[50:51]
	v_lshlrev_b64 v[52:53], 14, v[2:3]
	v_lshl_add_u64 v[38:39], v[36:37], 0, v[38:39]
	v_lshl_add_u64 v[40:41], v[36:37], 0, v[40:41]
	v_lshl_add_u64 v[42:43], v[36:37], 0, v[42:43]
	v_lshl_add_u64 v[44:45], v[36:37], 0, v[44:45]
	v_lshl_add_u64 v[46:47], v[36:37], 0, v[46:47]
	v_lshl_add_u64 v[48:49], v[36:37], 0, v[48:49]
	v_lshl_add_u64 v[50:51], v[36:37], 0, v[50:51]
	v_lshl_add_u64 v[36:37], v[36:37], 0, v[52:53]
	global_load_dword v2, v[38:39], off nt
	s_nop 0
	global_load_dword v38, v[40:41], off nt
	global_load_dword v39, v[42:43], off nt
	s_nop 0
	global_load_dword v40, v[44:45], off nt
	global_load_dword v41, v[46:47], off nt
	global_load_dword v42, v[48:49], off nt
	global_load_dword v43, v[50:51], off nt
	s_nop 0
	global_load_dword v36, v[36:37], off nt
	s_waitcnt vmcnt(30)
	ds_write2_b32 v58, v33, v35 offset1:66
	s_waitcnt vmcnt(28)
	ds_write2_b32 v58, v54, v55 offset0:132 offset1:198
	v_add_u32_e32 v33, 0x400, v58
	s_waitcnt vmcnt(26)
	ds_write2_b32 v33, v79, v80 offset0:8 offset1:74
	s_waitcnt vmcnt(24)
	ds_write2_b32 v33, v81, v82 offset0:140 offset1:206
	v_add_u32_e32 v33, 0x800, v58
	s_waitcnt vmcnt(22)
	ds_write2_b32 v33, v83, v84 offset0:16 offset1:82
	s_waitcnt vmcnt(20)
	ds_write2_b32 v33, v85, v86 offset0:148 offset1:214
	v_add_u32_e32 v33, 0xc00, v58
	s_waitcnt vmcnt(18)
	ds_write2_b32 v33, v87, v88 offset0:24 offset1:90
	s_waitcnt vmcnt(16)
	ds_write2_b32 v33, v89, v90 offset0:156 offset1:222
	v_add_u32_e32 v33, 0x1000, v58
	s_waitcnt vmcnt(14)
	ds_write2_b32 v33, v91, v92 offset0:32 offset1:98
	s_waitcnt vmcnt(12)
	ds_write2_b32 v33, v93, v94 offset0:164 offset1:230
	v_add_u32_e32 v33, 0x1400, v58
	s_waitcnt vmcnt(10)
	ds_write2_b32 v33, v95, v96 offset0:40 offset1:106
	s_waitcnt vmcnt(8)
	ds_write2_b32 v33, v97, v98 offset0:172 offset1:238
	v_add_u32_e32 v33, 0x1800, v58
	s_waitcnt vmcnt(6)
	ds_write2_b32 v33, v2, v38 offset0:48 offset1:114
	s_waitcnt vmcnt(4)
	ds_write2_b32 v33, v39, v40 offset0:180 offset1:246
	v_add_u32_e32 v2, 0x1c00, v58
	s_waitcnt vmcnt(2)
	ds_write2_b32 v2, v41, v42 offset0:56 offset1:122
	s_waitcnt vmcnt(0)
	ds_write2_b32 v2, v43, v36 offset0:188 offset1:254
	s_waitcnt lgkmcnt(0)
	ds_read2_b32 v[36:37], v75 offset1:33
	s_waitcnt lgkmcnt(0)
	v_cvt_pk_bf16_f32 v36, v36, v37
	ds_read2_b32 v[38:39], v75 offset0:66 offset1:99
	s_lshl_b32 s72, s1, 1
	v_or_b32_e32 v2, s0, v74
	s_waitcnt lgkmcnt(0)
	v_cvt_pk_bf16_f32 v37, v38, v39
	ds_read2_b32 v[38:39], v75 offset0:132 offset1:165
	v_lshl_add_u64 v[42:43], v[16:17], 0, s[72:73]
	v_lshlrev_b32_e32 v2, 12, v2
	s_waitcnt lgkmcnt(0)
	v_cvt_pk_bf16_f32 v38, v38, v39
	ds_read2_b32 v[40:41], v75 offset0:198 offset1:231
	s_waitcnt lgkmcnt(0)
	v_cvt_pk_bf16_f32 v39, v40, v41
	v_lshl_add_u64 v[44:45], v[42:43], 0, v[2:3]
	ds_read2_b32 v[40:41], v75 offset0:8 offset1:41
	global_store_dwordx4 v[44:45], v[36:39], off
	v_or_b32_e32 v2, s0, v76
	v_lshlrev_b32_e32 v2, 12, v2
	s_waitcnt lgkmcnt(0)
	v_cvt_pk_bf16_f32 v36, v40, v41
	ds_read2_b32 v[38:39], v75 offset0:74 offset1:107
	s_waitcnt lgkmcnt(0)
	v_cvt_pk_bf16_f32 v37, v38, v39
	ds_read2_b32 v[38:39], v75 offset0:140 offset1:173
	s_waitcnt lgkmcnt(0)
	v_cvt_pk_bf16_f32 v38, v38, v39
	ds_read2_b32 v[40:41], v75 offset0:206 offset1:239
	s_waitcnt lgkmcnt(0)
	v_cvt_pk_bf16_f32 v39, v40, v41
	v_lshl_add_u64 v[44:45], v[42:43], 0, v[2:3]
	ds_read2_b32 v[40:41], v75 offset0:16 offset1:49
	global_store_dwordx4 v[44:45], v[36:39], off
	v_or_b32_e32 v2, s0, v77
	v_lshlrev_b32_e32 v2, 12, v2
	s_waitcnt lgkmcnt(0)
	v_cvt_pk_bf16_f32 v36, v40, v41
	ds_read2_b32 v[38:39], v75 offset0:82 offset1:115
	s_waitcnt lgkmcnt(0)
	v_cvt_pk_bf16_f32 v37, v38, v39
	ds_read2_b32 v[38:39], v75 offset0:148 offset1:181
	s_waitcnt lgkmcnt(0)
	v_cvt_pk_bf16_f32 v38, v38, v39
	ds_read2_b32 v[40:41], v75 offset0:214 offset1:247
	s_waitcnt lgkmcnt(0)
	v_cvt_pk_bf16_f32 v39, v40, v41
	v_lshl_add_u64 v[44:45], v[42:43], 0, v[2:3]
	ds_read2_b32 v[40:41], v75 offset0:24 offset1:57
	global_store_dwordx4 v[44:45], v[36:39], off
	v_or_b32_e32 v2, s0, v78
	v_lshlrev_b32_e32 v2, 12, v2
	s_waitcnt lgkmcnt(0)
	v_cvt_pk_bf16_f32 v36, v40, v41
	ds_read2_b32 v[38:39], v75 offset0:90 offset1:123
	s_waitcnt lgkmcnt(0)
	v_cvt_pk_bf16_f32 v37, v38, v39
	ds_read2_b32 v[38:39], v75 offset0:156 offset1:189
	s_waitcnt lgkmcnt(0)
	v_cvt_pk_bf16_f32 v38, v38, v39
	ds_read2_b32 v[40:41], v75 offset0:222 offset1:255
	s_waitcnt lgkmcnt(0)
	v_cvt_pk_bf16_f32 v39, v40, v41
	v_lshl_add_u64 v[40:41], v[42:43], 0, v[2:3]
	global_store_dwordx4 v[40:41], v[36:39], off
	s_waitcnt lgkmcnt(0)

.LBB0_76:
	s_andn2_b64 vcc, exec, s[0:1]
	s_cbranch_vccnz .LBB0_78
	s_and_b32 s0, s75, 0x1fc0
	s_addk_i32 s0, 0xe900
	s_add_i32 s1, s26, 0xfffffc00
	s_and_b32 s2, s1, 0x7e0
	v_or_b32_e32 v2, s0, v56
	s_lshl_b32 s72, s2, 2
	v_or_b32_e32 v40, 2, v2
	v_mov_b32_e32 v41, v3
	v_or_b32_e32 v42, 4, v2
	v_mov_b32_e32 v43, v3
	v_or_b32_e32 v44, 6, v2
	v_mov_b32_e32 v45, v3
	v_or_b32_e32 v46, 8, v2
	v_mov_b32_e32 v47, v3
	v_or_b32_e32 v48, 10, v2
	v_mov_b32_e32 v49, v3
	v_or_b32_e32 v50, 12, v2
	v_mov_b32_e32 v51, v3
	v_lshl_add_u64 v[36:37], v[18:19], 0, s[72:73]
	v_lshlrev_b64 v[38:39], 13, v[2:3]
	v_lshlrev_b64 v[40:41], 13, v[40:41]
	v_lshlrev_b64 v[42:43], 13, v[42:43]
	v_lshlrev_b64 v[44:45], 13, v[44:45]
	v_lshlrev_b64 v[46:47], 13, v[46:47]
	v_lshlrev_b64 v[48:49], 13, v[48:49]
	v_lshlrev_b64 v[50:51], 13, v[50:51]
	v_or_b32_e32 v52, 14, v2
	v_mov_b32_e32 v53, v3
	v_lshl_add_u64 v[38:39], v[36:37], 0, v[38:39]
	v_lshl_add_u64 v[40:41], v[36:37], 0, v[40:41]
	v_lshl_add_u64 v[42:43], v[36:37], 0, v[42:43]
	v_lshl_add_u64 v[44:45], v[36:37], 0, v[44:45]
	v_lshl_add_u64 v[46:47], v[36:37], 0, v[46:47]
	v_lshl_add_u64 v[48:49], v[36:37], 0, v[48:49]
	v_lshl_add_u64 v[50:51], v[36:37], 0, v[50:51]
	v_lshlrev_b64 v[52:53], 13, v[52:53]
	v_lshl_add_u64 v[52:53], v[36:37], 0, v[52:53]
	global_load_dword v33, v[38:39], off nt
	global_load_dword v35, v[40:41], off nt
	global_load_dword v54, v[42:43], off nt
	global_load_dword v55, v[44:45], off nt
	global_load_dword v79, v[46:47], off nt
	global_load_dword v80, v[48:49], off nt
	global_load_dword v81, v[50:51], off nt
	global_load_dword v82, v[52:53], off nt
	v_or_b32_e32 v38, 16, v2
	v_mov_b32_e32 v39, v3
	v_or_b32_e32 v40, 18, v2
	v_mov_b32_e32 v41, v3
	v_or_b32_e32 v42, 20, v2
	v_mov_b32_e32 v43, v3
	v_or_b32_e32 v44, 22, v2
	v_mov_b32_e32 v45, v3
	v_or_b32_e32 v46, 24, v2
	v_mov_b32_e32 v47, v3
	v_or_b32_e32 v48, 26, v2
	v_mov_b32_e32 v49, v3
	v_or_b32_e32 v50, 28, v2
	v_mov_b32_e32 v51, v3
	v_lshlrev_b64 v[38:39], 13, v[38:39]
	v_lshlrev_b64 v[40:41], 13, v[40:41]
	v_lshlrev_b64 v[42:43], 13, v[42:43]
	v_lshlrev_b64 v[44:45], 13, v[44:45]
	v_lshlrev_b64 v[46:47], 13, v[46:47]
	v_lshlrev_b64 v[48:49], 13, v[48:49]
	v_lshlrev_b64 v[50:51], 13, v[50:51]
	v_or_b32_e32 v52, 30, v2
	v_mov_b32_e32 v53, v3
	v_lshl_add_u64 v[38:39], v[36:37], 0, v[38:39]
	v_lshl_add_u64 v[40:41], v[36:37], 0, v[40:41]
	v_lshl_add_u64 v[42:43], v[36:37], 0, v[42:43]
	v_lshl_add_u64 v[44:45], v[36:37], 0, v[44:45]
	v_lshl_add_u64 v[46:47], v[36:37], 0, v[46:47]
	v_lshl_add_u64 v[48:49], v[36:37], 0, v[48:49]
	v_lshl_add_u64 v[50:51], v[36:37], 0, v[50:51]
	v_lshlrev_b64 v[52:53], 13, v[52:53]
	v_lshl_add_u64 v[52:53], v[36:37], 0, v[52:53]
	global_load_dword v83, v[38:39], off nt
	global_load_dword v84, v[40:41], off nt
	global_load_dword v85, v[42:43], off nt
	global_load_dword v86, v[44:45], off nt
	global_load_dword v87, v[46:47], off nt
	global_load_dword v88, v[48:49], off nt
	global_load_dword v89, v[50:51], off nt
	global_load_dword v90, v[52:53], off nt
	v_or_b32_e32 v38, 32, v2
	v_mov_b32_e32 v39, v3
	v_or_b32_e32 v40, 34, v2
	v_mov_b32_e32 v41, v3
	v_or_b32_e32 v42, 36, v2
	v_mov_b32_e32 v43, v3
	v_or_b32_e32 v44, 38, v2
	v_mov_b32_e32 v45, v3
	v_or_b32_e32 v46, 40, v2
	v_mov_b32_e32 v47, v3
	v_or_b32_e32 v48, 42, v2
	v_mov_b32_e32 v49, v3
	v_or_b32_e32 v50, 44, v2
	v_mov_b32_e32 v51, v3
	v_lshlrev_b64 v[38:39], 13, v[38:39]
	v_lshlrev_b64 v[40:41], 13, v[40:41]
	v_lshlrev_b64 v[42:43], 13, v[42:43]
	v_lshlrev_b64 v[44:45], 13, v[44:45]
	v_lshlrev_b64 v[46:47], 13, v[46:47]
	v_lshlrev_b64 v[48:49], 13, v[48:49]
	v_lshlrev_b64 v[50:51], 13, v[50:51]
	v_or_b32_e32 v52, 46, v2
	v_mov_b32_e32 v53, v3
	v_lshl_add_u64 v[38:39], v[36:37], 0, v[38:39]
	v_lshl_add_u64 v[40:41], v[36:37], 0, v[40:41]
	v_lshl_add_u64 v[42:43], v[36:37], 0, v[42:43]
	v_lshl_add_u64 v[44:45], v[36:37], 0, v[44:45]
	v_lshl_add_u64 v[46:47], v[36:37], 0, v[46:47]
	v_lshl_add_u64 v[48:49], v[36:37], 0, v[48:49]
	v_lshl_add_u64 v[50:51], v[36:37], 0, v[50:51]
	v_lshlrev_b64 v[52:53], 13, v[52:53]
	v_lshl_add_u64 v[52:53], v[36:37], 0, v[52:53]
	global_load_dword v91, v[38:39], off nt
	global_load_dword v92, v[40:41], off nt
	global_load_dword v93, v[42:43], off nt
	global_load_dword v94, v[44:45], off nt
	global_load_dword v95, v[46:47], off nt
	global_load_dword v96, v[48:49], off nt
	global_load_dword v97, v[50:51], off nt
	global_load_dword v98, v[52:53], off nt
	v_or_b32_e32 v38, 48, v2
	v_mov_b32_e32 v39, v3
	v_or_b32_e32 v40, 50, v2
	v_mov_b32_e32 v41, v3
	v_or_b32_e32 v42, 52, v2
	v_mov_b32_e32 v43, v3
	v_or_b32_e32 v44, 54, v2
	v_mov_b32_e32 v45, v3
	v_or_b32_e32 v46, 56, v2
	v_mov_b32_e32 v47, v3
	v_or_b32_e32 v48, 58, v2
	v_mov_b32_e32 v49, v3
	v_or_b32_e32 v50, 60, v2
	v_mov_b32_e32 v51, v3
	v_or_b32_e32 v2, 62, v2
	v_lshlrev_b64 v[38:39], 13, v[38:39]
	v_lshlrev_b64 v[40:41], 13, v[40:41]
	v_lshlrev_b64 v[42:43], 13, v[42:43]
	v_lshlrev_b64 v[44:45], 13, v[44:45]
	v_lshlrev_b64 v[46:47], 13, v[46:47]
	v_lshlrev_b64 v[48:49], 13, v[48:49]
	v_lshlrev_b64 v[50:51], 13, v[50:51]
	v_lshlrev_b64 v[52:53], 13, v[2:3]
	v_lshl_add_u64 v[38:39], v[36:37], 0, v[38:39]
	v_lshl_add_u64 v[40:41], v[36:37], 0, v[40:41]
	v_lshl_add_u64 v[42:43], v[36:37], 0, v[42:43]
	v_lshl_add_u64 v[44:45], v[36:37], 0, v[44:45]
	v_lshl_add_u64 v[46:47], v[36:37], 0, v[46:47]
	v_lshl_add_u64 v[48:49], v[36:37], 0, v[48:49]
	v_lshl_add_u64 v[50:51], v[36:37], 0, v[50:51]
	v_lshl_add_u64 v[36:37], v[36:37], 0, v[52:53]
	global_load_dword v2, v[38:39], off nt
	s_nop 0
	global_load_dword v38, v[40:41], off nt
	global_load_dword v39, v[42:43], off nt
	s_nop 0
	global_load_dword v40, v[44:45], off nt
	global_load_dword v41, v[46:47], off nt
	global_load_dword v42, v[48:49], off nt
	global_load_dword v43, v[50:51], off nt
	s_nop 0
	global_load_dword v36, v[36:37], off nt
	s_waitcnt vmcnt(30)
	ds_write2_b32 v58, v33, v35 offset1:66
	s_waitcnt vmcnt(28)
	ds_write2_b32 v58, v54, v55 offset0:132 offset1:198
	v_add_u32_e32 v33, 0x400, v58
	s_waitcnt vmcnt(26)
	ds_write2_b32 v33, v79, v80 offset0:8 offset1:74
	s_waitcnt vmcnt(24)
	ds_write2_b32 v33, v81, v82 offset0:140 offset1:206
	v_add_u32_e32 v33, 0x800, v58
	s_waitcnt vmcnt(22)
	ds_write2_b32 v33, v83, v84 offset0:16 offset1:82
	s_waitcnt vmcnt(20)
	ds_write2_b32 v33, v85, v86 offset0:148 offset1:214
	v_add_u32_e32 v33, 0xc00, v58
	s_waitcnt vmcnt(18)
	ds_write2_b32 v33, v87, v88 offset0:24 offset1:90
	s_waitcnt vmcnt(16)
	ds_write2_b32 v33, v89, v90 offset0:156 offset1:222
	v_add_u32_e32 v33, 0x1000, v58
	s_waitcnt vmcnt(14)
	ds_write2_b32 v33, v91, v92 offset0:32 offset1:98
	s_waitcnt vmcnt(12)
	ds_write2_b32 v33, v93, v94 offset0:164 offset1:230
	v_add_u32_e32 v33, 0x1400, v58
	s_waitcnt vmcnt(10)
	ds_write2_b32 v33, v95, v96 offset0:40 offset1:106
	s_waitcnt vmcnt(8)
	ds_write2_b32 v33, v97, v98 offset0:172 offset1:238
	v_add_u32_e32 v33, 0x1800, v58
	s_waitcnt vmcnt(6)
	ds_write2_b32 v33, v2, v38 offset0:48 offset1:114
	s_waitcnt vmcnt(4)
	ds_write2_b32 v33, v39, v40 offset0:180 offset1:246
	v_add_u32_e32 v2, 0x1c00, v58
	s_waitcnt vmcnt(2)
	ds_write2_b32 v2, v41, v42 offset0:56 offset1:122
	s_waitcnt vmcnt(0)
	ds_write2_b32 v2, v43, v36 offset0:188 offset1:254
	s_waitcnt lgkmcnt(0)
	ds_read2_b32 v[36:37], v75 offset1:33
	s_waitcnt lgkmcnt(0)
	v_cvt_pk_bf16_f32 v36, v36, v37
	ds_read2_b32 v[38:39], v75 offset0:66 offset1:99
	s_mov_b32 s1, s73
	v_or_b32_e32 v2, s2, v74
	s_waitcnt lgkmcnt(0)
	v_cvt_pk_bf16_f32 v37, v38, v39
	ds_read2_b32 v[38:39], v75 offset0:132 offset1:165
	v_lshl_add_u64 v[42:43], s[0:1], 1, v[20:21]
	v_lshlrev_b32_e32 v2, 12, v2
	s_waitcnt lgkmcnt(0)
	v_cvt_pk_bf16_f32 v38, v38, v39
	ds_read2_b32 v[40:41], v75 offset0:198 offset1:231
	s_waitcnt lgkmcnt(0)
	v_cvt_pk_bf16_f32 v39, v40, v41
	v_lshl_add_u64 v[44:45], v[42:43], 0, v[2:3]
	ds_read2_b32 v[40:41], v75 offset0:8 offset1:41
	global_store_dwordx4 v[44:45], v[36:39], off
	v_or_b32_e32 v2, s2, v76
	v_lshlrev_b32_e32 v2, 12, v2
	s_waitcnt lgkmcnt(0)
	v_cvt_pk_bf16_f32 v36, v40, v41
	ds_read2_b32 v[38:39], v75 offset0:74 offset1:107
	s_waitcnt lgkmcnt(0)
	v_cvt_pk_bf16_f32 v37, v38, v39
	ds_read2_b32 v[38:39], v75 offset0:140 offset1:173
	s_waitcnt lgkmcnt(0)
	v_cvt_pk_bf16_f32 v38, v38, v39
	ds_read2_b32 v[40:41], v75 offset0:206 offset1:239
	s_waitcnt lgkmcnt(0)
	v_cvt_pk_bf16_f32 v39, v40, v41
	v_lshl_add_u64 v[44:45], v[42:43], 0, v[2:3]
	ds_read2_b32 v[40:41], v75 offset0:16 offset1:49
	global_store_dwordx4 v[44:45], v[36:39], off
	v_or_b32_e32 v2, s2, v77
	v_lshlrev_b32_e32 v2, 12, v2
	s_waitcnt lgkmcnt(0)
	v_cvt_pk_bf16_f32 v36, v40, v41
	ds_read2_b32 v[38:39], v75 offset0:82 offset1:115
	s_waitcnt lgkmcnt(0)
	v_cvt_pk_bf16_f32 v37, v38, v39
	ds_read2_b32 v[38:39], v75 offset0:148 offset1:181
	s_waitcnt lgkmcnt(0)
	v_cvt_pk_bf16_f32 v38, v38, v39
	ds_read2_b32 v[40:41], v75 offset0:214 offset1:247
	s_waitcnt lgkmcnt(0)
	v_cvt_pk_bf16_f32 v39, v40, v41
	v_lshl_add_u64 v[44:45], v[42:43], 0, v[2:3]
	ds_read2_b32 v[40:41], v75 offset0:24 offset1:57
	global_store_dwordx4 v[44:45], v[36:39], off
	v_or_b32_e32 v2, s2, v78
	v_lshlrev_b32_e32 v2, 12, v2
	s_waitcnt lgkmcnt(0)
	v_cvt_pk_bf16_f32 v36, v40, v41
	ds_read2_b32 v[38:39], v75 offset0:90 offset1:123
	s_waitcnt lgkmcnt(0)
	v_cvt_pk_bf16_f32 v37, v38, v39
	ds_read2_b32 v[38:39], v75 offset0:156 offset1:189
	s_waitcnt lgkmcnt(0)
	v_cvt_pk_bf16_f32 v38, v38, v39
	ds_read2_b32 v[40:41], v75 offset0:222 offset1:255
	s_waitcnt lgkmcnt(0)
	v_cvt_pk_bf16_f32 v39, v40, v41
	v_lshl_add_u64 v[40:41], v[42:43], 0, v[2:3]
	global_store_dwordx4 v[40:41], v[36:39], off
	s_waitcnt lgkmcnt(0)

.LBB0_79:
	s_andn2_b64 vcc, exec, s[0:1]
	s_cbranch_vccnz .LBB0_105
	s_add_i32 s0, s75, 0xfffff100
	s_add_i32 s1, s26, 0xfffffc00
	s_and_b32 s2, s1, 0x7e0
	s_and_b32 s72, s0, 0xffffffc0
	s_cmpk_lt_u32 s0, 0x400
	v_or_b32_e32 v2, s72, v56
	s_cselect_b32 s11, s7, s21
	s_cselect_b32 s10, s6, s20
	s_lshl_b32 s0, s2, 2
	s_mov_b32 s1, s73
	v_or_b32_e32 v48, 10, v2
	v_mov_b32_e32 v49, v3
	v_or_b32_e32 v50, 12, v2
	v_mov_b32_e32 v51, v3
	v_lshl_add_u64 v[36:37], v[22:23], 0, s[0:1]
	v_lshlrev_b64 v[38:39], 13, v[2:3]
	v_or_b32_e32 v40, 2, v2
	v_mov_b32_e32 v41, v3
	v_or_b32_e32 v42, 4, v2
	v_mov_b32_e32 v43, v3
	v_or_b32_e32 v44, 6, v2
	v_mov_b32_e32 v45, v3
	v_or_b32_e32 v46, 8, v2
	v_mov_b32_e32 v47, v3
	v_lshlrev_b64 v[48:49], 13, v[48:49]
	v_lshlrev_b64 v[50:51], 13, v[50:51]
	v_or_b32_e32 v52, 14, v2
	v_mov_b32_e32 v53, v3
	v_lshl_add_u64 v[38:39], v[36:37], 0, v[38:39]
	v_lshlrev_b64 v[40:41], 13, v[40:41]
	v_lshlrev_b64 v[42:43], 13, v[42:43]
	v_lshlrev_b64 v[44:45], 13, v[44:45]
	v_lshlrev_b64 v[46:47], 13, v[46:47]
	v_lshl_add_u64 v[48:49], v[36:37], 0, v[48:49]
	v_lshl_add_u64 v[50:51], v[36:37], 0, v[50:51]
	v_lshlrev_b64 v[52:53], 13, v[52:53]
	v_lshl_add_u64 v[40:41], v[36:37], 0, v[40:41]
	v_lshl_add_u64 v[42:43], v[36:37], 0, v[42:43]
	v_lshl_add_u64 v[44:45], v[36:37], 0, v[44:45]
	v_lshl_add_u64 v[46:47], v[36:37], 0, v[46:47]
	v_lshl_add_u64 v[54:55], v[36:37], 0, v[52:53]
	global_load_dword v91, v[38:39], off nt
	global_load_dword v92, v[40:41], off nt
	global_load_dword v52, v[42:43], off nt
	global_load_dword v53, v[44:45], off nt
	global_load_dword v89, v[46:47], off nt
	global_load_dword v90, v[48:49], off nt
	s_nop 0
	global_load_dword v50, v[50:51], off nt
	s_nop 0
	global_load_dword v51, v[54:55], off nt
	v_or_b32_e32 v48, 26, v2
	v_mov_b32_e32 v49, v3
	v_lshlrev_b64 v[48:49], 13, v[48:49]
	v_lshl_add_u64 v[54:55], v[36:37], 0, v[48:49]
	v_or_b32_e32 v48, 28, v2
	v_mov_b32_e32 v49, v3
	v_or_b32_e32 v38, 16, v2
	v_mov_b32_e32 v39, v3
	v_or_b32_e32 v44, 22, v2
	v_mov_b32_e32 v45, v3
	v_or_b32_e32 v46, 24, v2
	v_mov_b32_e32 v47, v3
	v_lshlrev_b64 v[48:49], 13, v[48:49]
	v_lshlrev_b64 v[38:39], 13, v[38:39]
	v_or_b32_e32 v40, 18, v2
	v_mov_b32_e32 v41, v3
	v_or_b32_e32 v42, 20, v2
	v_mov_b32_e32 v43, v3
	v_lshlrev_b64 v[44:45], 13, v[44:45]
	v_lshlrev_b64 v[46:47], 13, v[46:47]
	v_lshl_add_u64 v[80:81], v[36:37], 0, v[48:49]
	v_or_b32_e32 v48, 30, v2
	v_mov_b32_e32 v49, v3
	v_lshl_add_u64 v[38:39], v[36:37], 0, v[38:39]
	v_lshlrev_b64 v[40:41], 13, v[40:41]
	v_lshlrev_b64 v[42:43], 13, v[42:43]
	v_lshl_add_u64 v[44:45], v[36:37], 0, v[44:45]
	v_lshl_add_u64 v[46:47], v[36:37], 0, v[46:47]
	v_lshlrev_b64 v[48:49], 13, v[48:49]
	v_lshl_add_u64 v[40:41], v[36:37], 0, v[40:41]
	v_lshl_add_u64 v[42:43], v[36:37], 0, v[42:43]
	v_lshl_add_u64 v[82:83], v[36:37], 0, v[48:49]
	global_load_dword v87, v[38:39], off nt
	global_load_dword v88, v[40:41], off nt
	global_load_dword v48, v[42:43], off nt
	global_load_dword v49, v[44:45], off nt
	global_load_dword v85, v[46:47], off nt
	global_load_dword v86, v[54:55], off nt
	s_nop 0
	global_load_dword v46, v[80:81], off nt
	global_load_dword v47, v[82:83], off nt
	v_or_b32_e32 v44, 38, v2
	v_mov_b32_e32 v45, v3
	v_lshlrev_b64 v[44:45], 13, v[44:45]
	v_lshl_add_u64 v[54:55], v[36:37], 0, v[44:45]
	v_or_b32_e32 v44, 40, v2
	v_mov_b32_e32 v45, v3
	v_lshlrev_b64 v[44:45], 13, v[44:45]
	v_lshl_add_u64 v[80:81], v[36:37], 0, v[44:45]
	v_or_b32_e32 v44, 42, v2
	v_mov_b32_e32 v45, v3
	v_lshlrev_b64 v[44:45], 13, v[44:45]
	v_lshl_add_u64 v[94:95], v[36:37], 0, v[44:45]
	v_or_b32_e32 v44, 44, v2
	v_mov_b32_e32 v45, v3
	v_or_b32_e32 v38, 32, v2
	v_mov_b32_e32 v39, v3
	v_or_b32_e32 v40, 34, v2
	v_mov_b32_e32 v41, v3
	v_or_b32_e32 v42, 36, v2
	v_mov_b32_e32 v43, v3
	v_lshlrev_b64 v[44:45], 13, v[44:45]
	v_lshlrev_b64 v[38:39], 13, v[38:39]
	v_lshlrev_b64 v[40:41], 13, v[40:41]
	v_lshlrev_b64 v[42:43], 13, v[42:43]
	v_lshl_add_u64 v[96:97], v[36:37], 0, v[44:45]
	v_or_b32_e32 v44, 46, v2
	v_mov_b32_e32 v45, v3
	v_lshl_add_u64 v[38:39], v[36:37], 0, v[38:39]
	v_lshl_add_u64 v[40:41], v[36:37], 0, v[40:41]
	v_lshl_add_u64 v[42:43], v[36:37], 0, v[42:43]
	v_lshlrev_b64 v[44:45], 13, v[44:45]
	v_lshl_add_u64 v[98:99], v[36:37], 0, v[44:45]
	global_load_dword v83, v[38:39], off nt
	global_load_dword v84, v[40:41], off nt
	global_load_dword v44, v[42:43], off nt
	global_load_dword v45, v[54:55], off nt
	s_nop 0
	global_load_dword v81, v[80:81], off nt
	s_nop 0
	global_load_dword v82, v[94:95], off nt
	global_load_dword v42, v[96:97], off nt
	global_load_dword v43, v[98:99], off nt
	v_or_b32_e32 v38, 48, v2
	v_mov_b32_e32 v39, v3
	v_or_b32_e32 v40, 50, v2
	v_mov_b32_e32 v41, v3
	v_lshlrev_b64 v[38:39], 13, v[38:39]
	v_lshlrev_b64 v[40:41], 13, v[40:41]
	v_or_b32_e32 v54, 52, v2
	v_mov_b32_e32 v55, v3
	v_or_b32_e32 v94, 54, v2
	v_mov_b32_e32 v95, v3
	v_or_b32_e32 v96, 56, v2
	v_mov_b32_e32 v97, v3
	v_or_b32_e32 v98, 58, v2
	v_mov_b32_e32 v99, v3
	v_or_b32_e32 v100, 60, v2
	v_mov_b32_e32 v101, v3
	v_or_b32_e32 v102, 62, v2
	v_mov_b32_e32 v103, v3
	v_lshl_add_u64 v[38:39], v[36:37], 0, v[38:39]
	v_lshl_add_u64 v[40:41], v[36:37], 0, v[40:41]
	v_lshlrev_b64 v[54:55], 13, v[54:55]
	v_lshlrev_b64 v[94:95], 13, v[94:95]
	v_lshlrev_b64 v[96:97], 13, v[96:97]
	v_lshlrev_b64 v[98:99], 13, v[98:99]
	v_lshlrev_b64 v[100:101], 13, v[100:101]
	v_lshlrev_b64 v[102:103], 13, v[102:103]
	v_lshl_add_u64 v[54:55], v[36:37], 0, v[54:55]
	v_lshl_add_u64 v[94:95], v[36:37], 0, v[94:95]
	v_lshl_add_u64 v[96:97], v[36:37], 0, v[96:97]
	v_lshl_add_u64 v[98:99], v[36:37], 0, v[98:99]
	v_lshl_add_u64 v[100:101], v[36:37], 0, v[100:101]
	v_lshl_add_u64 v[102:103], v[36:37], 0, v[102:103]
	global_load_dword v79, v[38:39], off nt
	global_load_dword v80, v[40:41], off nt
	s_nop 0
	global_load_dword v40, v[54:55], off nt
	global_load_dword v41, v[94:95], off nt
	global_load_dword v33, v[96:97], off nt
	global_load_dword v35, v[98:99], off nt
	global_load_dword v36, v[100:101], off nt
	global_load_dword v37, v[102:103], off nt
	s_cmp_lg_u64 s[10:11], 0
	s_cselect_b64 s[18:19], -1, 0
	s_cmp_eq_u64 s[10:11], 0
	v_add_u32_e32 v38, s72, v56
	v_add_u32_e32 v93, v57, v59
	s_cbranch_scc1 .LBB0_111
	v_lshl_add_u64 v[54:55], v[2:3], 2, s[10:11]
	v_mov_b32_e32 v39, v3
	v_lshl_add_u64 v[94:95], v[38:39], 2, s[10:11]
	global_load_dword v2, v[54:55], off nt
	global_load_dword v39, v[94:95], off offset:8 nt
	s_nop 0
	global_load_dword v54, v[94:95], off offset:16 nt
	global_load_dword v55, v[94:95], off offset:24 nt
	s_waitcnt vmcnt(3)
	v_mul_f32_e32 v2, v91, v2
	s_waitcnt vmcnt(2)
	v_mul_f32_e32 v39, v92, v39
	ds_write_b32 v58, v2
	s_waitcnt vmcnt(0)
	v_pk_mul_f32 v[54:55], v[52:53], v[54:55]
	ds_write_b32 v93, v39
	s_cbranch_execnz .LBB0_83

.LBB0_83:
	v_add_u32_e32 v2, v57, v60
	ds_write2_b32 v2, v54, v55 offset1:66
	v_cndmask_b32_e64 v2, 0, 1, s[18:19]
	v_cmp_ne_u32_e64 s[0:1], 1, v2
	s_andn2_b64 vcc, exec, s[18:19]
	v_add_u32_e32 v2, v57, v61
	s_cbranch_vccnz .LBB0_112
	v_mov_b32_e32 v39, v3
	s_waitcnt vmcnt(28)
	v_lshl_add_u64 v[52:53], v[38:39], 2, s[10:11]
	global_load_dword v39, v[52:53], off offset:32 nt
	global_load_dword v91, v[52:53], off offset:40 nt
	global_load_dword v54, v[52:53], off offset:48 nt
	global_load_dword v55, v[52:53], off offset:56 nt
	s_waitcnt vmcnt(3)
	v_mul_f32_e32 v39, v89, v39
	s_waitcnt vmcnt(2)
	v_mul_f32_e32 v91, v90, v91
	ds_write2_b32 v2, v39, v91 offset1:66
	s_waitcnt vmcnt(0)
	v_pk_mul_f32 v[52:53], v[50:51], v[54:55]
	s_cbranch_execnz .LBB0_86

.LBB0_86:
	v_add_u32_e32 v2, v57, v62
	s_waitcnt vmcnt(28)
	ds_write2_b32 v2, v52, v53 offset1:66
	s_and_b64 vcc, exec, s[0:1]
	v_add_u32_e32 v2, v57, v63
	s_cbranch_vccnz .LBB0_113
	v_mov_b32_e32 v39, v3
	s_waitcnt vmcnt(24)
	v_lshl_add_u64 v[50:51], v[38:39], 2, s[10:11]
	global_load_dword v39, v[50:51], off offset:64 nt
	global_load_dword v54, v[50:51], off offset:72 nt
	global_load_dword v52, v[50:51], off offset:80 nt
	global_load_dword v53, v[50:51], off offset:88 nt
	s_waitcnt vmcnt(3)
	v_mul_f32_e32 v39, v87, v39
	s_waitcnt vmcnt(2)
	v_mul_f32_e32 v54, v88, v54
	ds_write2_b32 v2, v39, v54 offset1:66
	s_waitcnt vmcnt(0)
	v_pk_mul_f32 v[50:51], v[48:49], v[52:53]
	s_cbranch_execnz .LBB0_89

.LBB0_89:
	v_add_u32_e32 v2, v57, v64
	s_waitcnt vmcnt(24)
	ds_write2_b32 v2, v50, v51 offset1:66
	s_and_b64 vcc, exec, s[0:1]
	v_add_u32_e32 v2, v57, v65
	s_cbranch_vccnz .LBB0_114
	v_mov_b32_e32 v39, v3
	s_waitcnt vmcnt(20)
	v_lshl_add_u64 v[48:49], v[38:39], 2, s[10:11]
	global_load_dword v39, v[48:49], off offset:96 nt
	global_load_dword v52, v[48:49], off offset:104 nt
	global_load_dword v50, v[48:49], off offset:112 nt
	global_load_dword v51, v[48:49], off offset:120 nt
	s_waitcnt vmcnt(3)
	v_mul_f32_e32 v39, v85, v39
	s_waitcnt vmcnt(2)
	v_mul_f32_e32 v52, v86, v52
	ds_write2_b32 v2, v39, v52 offset1:66
	s_waitcnt vmcnt(0)
	v_pk_mul_f32 v[48:49], v[46:47], v[50:51]
	s_cbranch_execnz .LBB0_92

.LBB0_92:
	v_add_u32_e32 v2, v57, v67
	s_waitcnt vmcnt(20)
	ds_write2_b32 v2, v48, v49 offset1:66
	s_and_b64 vcc, exec, s[0:1]
	v_add_u32_e32 v2, v57, v69
	s_cbranch_vccnz .LBB0_115
	v_mov_b32_e32 v39, v3
	s_waitcnt vmcnt(16)
	v_lshl_add_u64 v[46:47], v[38:39], 2, s[10:11]
	global_load_dword v39, v[46:47], off offset:128 nt
	global_load_dword v50, v[46:47], off offset:136 nt
	global_load_dword v48, v[46:47], off offset:144 nt
	global_load_dword v49, v[46:47], off offset:152 nt
	s_waitcnt vmcnt(3)
	v_mul_f32_e32 v39, v83, v39
	s_waitcnt vmcnt(2)
	v_mul_f32_e32 v50, v84, v50
	ds_write2_b32 v2, v39, v50 offset1:66
	s_waitcnt vmcnt(0)
	v_pk_mul_f32 v[46:47], v[44:45], v[48:49]
	s_cbranch_execnz .LBB0_95

.LBB0_95:
	v_add_u32_e32 v2, v57, v70
	s_waitcnt vmcnt(16)
	ds_write2_b32 v2, v46, v47 offset1:66
	s_and_b64 vcc, exec, s[0:1]
	v_add_u32_e32 v2, v57, v71
	s_cbranch_vccnz .LBB0_116
	v_mov_b32_e32 v39, v3
	s_waitcnt vmcnt(12)
	v_lshl_add_u64 v[44:45], v[38:39], 2, s[10:11]
	global_load_dword v39, v[44:45], off offset:160 nt
	global_load_dword v48, v[44:45], off offset:168 nt
	global_load_dword v46, v[44:45], off offset:176 nt
	global_load_dword v47, v[44:45], off offset:184 nt
	s_waitcnt vmcnt(3)
	v_mul_f32_e32 v39, v81, v39
	s_waitcnt vmcnt(2)
	v_mul_f32_e32 v48, v82, v48
	ds_write2_b32 v2, v39, v48 offset1:66
	s_waitcnt vmcnt(0)
	v_pk_mul_f32 v[44:45], v[42:43], v[46:47]
	s_cbranch_execnz .LBB0_98

.LBB0_98:
	v_add_u32_e32 v2, v57, v72
	s_waitcnt vmcnt(12)
	ds_write2_b32 v2, v44, v45 offset1:66
	s_and_b64 vcc, exec, s[0:1]
	v_add_u32_e32 v2, v57, v73
	s_cbranch_vccnz .LBB0_117
	v_mov_b32_e32 v39, v3
	s_waitcnt vmcnt(8)
	v_lshl_add_u64 v[42:43], v[38:39], 2, s[10:11]
	global_load_dword v39, v[42:43], off offset:192 nt
	global_load_dword v46, v[42:43], off offset:200 nt
	global_load_dword v44, v[42:43], off offset:208 nt
	global_load_dword v45, v[42:43], off offset:216 nt
	s_waitcnt vmcnt(3)
	v_mul_f32_e32 v39, v79, v39
	s_waitcnt vmcnt(2)
	v_mul_f32_e32 v46, v80, v46
	ds_write2_b32 v2, v39, v46 offset1:66
	s_waitcnt vmcnt(0)
	v_pk_mul_f32 v[42:43], v[40:41], v[44:45]
	s_cbranch_execnz .LBB0_101

.LBB0_101:
	s_waitcnt vmcnt(8)
	ds_write2_b32 v2, v42, v43 offset0:132 offset1:198
	s_and_b64 vcc, exec, s[0:1]
	v_add_u32_e32 v2, 0x400, v2
	s_cbranch_vccnz .LBB0_118
	v_mov_b32_e32 v39, v3
	v_lshl_add_u64 v[38:39], v[38:39], 2, s[10:11]
	global_load_dword v42, v[38:39], off offset:224 nt
	global_load_dword v43, v[38:39], off offset:232 nt
	global_load_dword v40, v[38:39], off offset:240 nt
	global_load_dword v41, v[38:39], off offset:248 nt
	s_waitcnt vmcnt(3)
	v_mul_f32_e32 v42, v33, v42
	s_waitcnt vmcnt(2)
	v_mul_f32_e32 v43, v35, v43
	ds_write2_b32 v2, v42, v43 offset0:8 offset1:74
	s_waitcnt vmcnt(0)
	v_pk_mul_f32 v[38:39], v[36:37], v[40:41]
	s_cbranch_execnz .LBB0_104

.LBB0_106:
	s_andn2_b64 vcc, exec, s[0:1]
	s_cbranch_vccnz .LBB0_108
	s_add_i32 s0, s26, 0xfffffc00
	s_and_b32 s0, s0, 0x3e0
	s_and_b32 s1, s65, 0x1fc0
	v_readlane_b32 s76, v252, 1
	s_add_i32 s72, s1, 0xffffea00
	s_lshl_b32 s1, s0, 2
	v_readlane_b32 s84, v252, 9
	v_readlane_b32 s85, v252, 10
	s_add_u32 s2, s84, s1
	s_addc_u32 s3, s85, 0
	v_mov_b32_e32 v35, v3
	v_or_b32_e32 v2, s72, v56
	v_lshl_add_u64 v[36:37], s[2:3], 0, v[34:35]
	v_lshl_add_u64 v[36:37], v[36:37], 0, s[8:9]
	v_or_b32_e32 v33, 2, v2
	v_mad_u64_u32 v[40:41], s[2:3], v33, s74, v[36:37]
	v_or_b32_e32 v33, 4, v2
	v_mad_u64_u32 v[42:43], s[2:3], v33, s74, v[36:37]
	v_or_b32_e32 v33, 6, v2
	v_mad_u64_u32 v[44:45], s[2:3], v33, s74, v[36:37]
	v_or_b32_e32 v33, 8, v2
	v_mad_u64_u32 v[46:47], s[2:3], v33, s74, v[36:37]
	v_or_b32_e32 v33, 10, v2
	v_mad_u64_u32 v[48:49], s[2:3], v33, s74, v[36:37]
	v_or_b32_e32 v33, 12, v2
	v_mad_u64_u32 v[50:51], s[2:3], v33, s74, v[36:37]
	v_or_b32_e32 v33, 14, v2
	v_mad_u64_u32 v[38:39], s[2:3], v2, s74, v[36:37]
	v_mad_u64_u32 v[52:53], s[2:3], v33, s74, v[36:37]
	global_load_dword v33, v[38:39], off nt
	global_load_dword v35, v[40:41], off nt
	global_load_dword v54, v[42:43], off nt
	global_load_dword v55, v[44:45], off nt
	global_load_dword v79, v[46:47], off nt
	global_load_dword v80, v[48:49], off nt
	global_load_dword v81, v[50:51], off nt
	global_load_dword v82, v[52:53], off nt
	v_or_b32_e32 v38, 16, v2
	v_or_b32_e32 v40, 18, v2
	v_or_b32_e32 v42, 20, v2
	v_or_b32_e32 v44, 22, v2
	v_or_b32_e32 v46, 24, v2
	v_or_b32_e32 v48, 26, v2
	v_or_b32_e32 v50, 28, v2
	v_or_b32_e32 v52, 30, v2
	v_mad_u64_u32 v[38:39], s[2:3], v38, s74, v[36:37]
	v_mad_u64_u32 v[40:41], s[2:3], v40, s74, v[36:37]
	v_mad_u64_u32 v[42:43], s[2:3], v42, s74, v[36:37]
	v_mad_u64_u32 v[44:45], s[2:3], v44, s74, v[36:37]
	v_mad_u64_u32 v[46:47], s[2:3], v46, s74, v[36:37]
	v_mad_u64_u32 v[48:49], s[2:3], v48, s74, v[36:37]
	v_mad_u64_u32 v[50:51], s[2:3], v50, s74, v[36:37]
	v_mad_u64_u32 v[52:53], s[2:3], v52, s74, v[36:37]
	global_load_dword v83, v[38:39], off nt
	global_load_dword v84, v[40:41], off nt
	global_load_dword v85, v[42:43], off nt
	global_load_dword v86, v[44:45], off nt
	global_load_dword v87, v[46:47], off nt
	global_load_dword v88, v[48:49], off nt
	global_load_dword v89, v[50:51], off nt
	global_load_dword v90, v[52:53], off nt
	v_or_b32_e32 v38, 32, v2
	v_or_b32_e32 v40, 34, v2
	v_or_b32_e32 v42, 36, v2
	v_or_b32_e32 v44, 38, v2
	v_or_b32_e32 v46, 40, v2
	v_or_b32_e32 v48, 42, v2
	v_or_b32_e32 v50, 44, v2
	v_or_b32_e32 v52, 46, v2
	v_mad_u64_u32 v[38:39], s[2:3], v38, s74, v[36:37]
	v_mad_u64_u32 v[40:41], s[2:3], v40, s74, v[36:37]
	v_mad_u64_u32 v[42:43], s[2:3], v42, s74, v[36:37]
	v_mad_u64_u32 v[44:45], s[2:3], v44, s74, v[36:37]
	v_mad_u64_u32 v[46:47], s[2:3], v46, s74, v[36:37]
	v_mad_u64_u32 v[48:49], s[2:3], v48, s74, v[36:37]
	v_mad_u64_u32 v[50:51], s[2:3], v50, s74, v[36:37]
	v_mad_u64_u32 v[52:53], s[2:3], v52, s74, v[36:37]
	global_load_dword v91, v[38:39], off nt
	global_load_dword v92, v[40:41], off nt
	global_load_dword v93, v[42:43], off nt
	global_load_dword v94, v[44:45], off nt
	global_load_dword v95, v[46:47], off nt
	global_load_dword v96, v[48:49], off nt
	global_load_dword v97, v[50:51], off nt
	s_nop 0
	global_load_dword v52, v[52:53], off nt
	v_or_b32_e32 v38, 48, v2
	v_or_b32_e32 v40, 50, v2
	v_or_b32_e32 v42, 52, v2
	v_or_b32_e32 v44, 54, v2
	v_or_b32_e32 v46, 56, v2
	v_or_b32_e32 v48, 58, v2
	v_or_b32_e32 v50, 60, v2
	v_or_b32_e32 v2, 62, v2
	v_mad_u64_u32 v[38:39], s[2:3], v38, s74, v[36:37]
	v_mad_u64_u32 v[40:41], s[2:3], v40, s74, v[36:37]
	v_mad_u64_u32 v[42:43], s[2:3], v42, s74, v[36:37]
	v_mad_u64_u32 v[44:45], s[2:3], v44, s74, v[36:37]
	v_mad_u64_u32 v[46:47], s[2:3], v46, s74, v[36:37]
	v_mad_u64_u32 v[48:49], s[2:3], v48, s74, v[36:37]
	v_mad_u64_u32 v[50:51], s[2:3], v50, s74, v[36:37]
	v_mad_u64_u32 v[36:37], s[2:3], v2, s74, v[36:37]
	global_load_dword v2, v[38:39], off nt
	s_nop 0
	global_load_dword v38, v[40:41], off nt
	global_load_dword v39, v[42:43], off nt
	s_nop 0
	global_load_dword v40, v[44:45], off nt
	global_load_dword v41, v[46:47], off nt
	global_load_dword v42, v[48:49], off nt
	global_load_dword v43, v[50:51], off nt
	s_nop 0
	global_load_dword v36, v[36:37], off nt
	s_waitcnt vmcnt(30)
	ds_write2_b32 v58, v33, v35 offset1:66
	s_waitcnt vmcnt(28)
	ds_write2_b32 v58, v54, v55 offset0:132 offset1:198
	v_add_u32_e32 v33, 0x400, v58
	s_waitcnt vmcnt(26)
	ds_write2_b32 v33, v79, v80 offset0:8 offset1:74
	s_waitcnt vmcnt(24)
	ds_write2_b32 v33, v81, v82 offset0:140 offset1:206
	v_add_u32_e32 v33, 0x800, v58
	s_waitcnt vmcnt(22)
	ds_write2_b32 v33, v83, v84 offset0:16 offset1:82
	s_waitcnt vmcnt(20)
	ds_write2_b32 v33, v85, v86 offset0:148 offset1:214
	v_add_u32_e32 v33, 0xc00, v58
	s_waitcnt vmcnt(18)
	ds_write2_b32 v33, v87, v88 offset0:24 offset1:90
	s_waitcnt vmcnt(16)
	ds_write2_b32 v33, v89, v90 offset0:156 offset1:222
	v_add_u32_e32 v33, 0x1000, v58
	s_waitcnt vmcnt(14)
	ds_write2_b32 v33, v91, v92 offset0:32 offset1:98
	s_waitcnt vmcnt(12)
	ds_write2_b32 v33, v93, v94 offset0:164 offset1:230
	v_add_u32_e32 v33, 0x1400, v58
	s_waitcnt vmcnt(10)
	ds_write2_b32 v33, v95, v96 offset0:40 offset1:106
	s_waitcnt vmcnt(8)
	ds_write2_b32 v33, v97, v52 offset0:172 offset1:238
	v_add_u32_e32 v33, 0x1800, v58
	s_waitcnt vmcnt(6)
	ds_write2_b32 v33, v2, v38 offset0:48 offset1:114
	s_waitcnt vmcnt(4)
	ds_write2_b32 v33, v39, v40 offset0:180 offset1:246
	v_add_u32_e32 v2, 0x1c00, v58
	s_waitcnt vmcnt(2)
	ds_write2_b32 v2, v41, v42 offset0:56 offset1:122
	s_waitcnt vmcnt(0)
	ds_write2_b32 v2, v43, v36 offset0:188 offset1:254
	s_waitcnt lgkmcnt(0)
	ds_read2_b32 v[36:37], v75 offset1:33
	s_waitcnt lgkmcnt(0)
	v_cvt_pk_bf16_f32 v36, v36, v37
	ds_read2_b32 v[38:39], v75 offset0:66 offset1:99
	v_or_b32_e32 v2, s0, v74
	s_waitcnt lgkmcnt(0)
	v_cvt_pk_bf16_f32 v37, v38, v39
	ds_read2_b32 v[38:39], v75 offset0:132 offset1:165
	v_lshl_add_u64 v[42:43], s[72:73], 1, v[26:27]
	v_lshlrev_b32_e32 v2, 12, v2
	s_waitcnt lgkmcnt(0)
	v_cvt_pk_bf16_f32 v38, v38, v39
	ds_read2_b32 v[40:41], v75 offset0:198 offset1:231
	s_waitcnt lgkmcnt(0)
	v_cvt_pk_bf16_f32 v39, v40, v41
	v_lshl_add_u64 v[44:45], v[42:43], 0, v[2:3]
	ds_read2_b32 v[40:41], v75 offset0:8 offset1:41
	global_store_dwordx4 v[44:45], v[36:39], off
	v_or_b32_e32 v2, s0, v76
	v_lshlrev_b32_e32 v2, 12, v2
	s_waitcnt lgkmcnt(0)
	v_cvt_pk_bf16_f32 v36, v40, v41
	ds_read2_b32 v[38:39], v75 offset0:74 offset1:107
	s_waitcnt lgkmcnt(0)
	v_cvt_pk_bf16_f32 v37, v38, v39
	ds_read2_b32 v[38:39], v75 offset0:140 offset1:173
	s_waitcnt lgkmcnt(0)
	v_cvt_pk_bf16_f32 v38, v38, v39
	ds_read2_b32 v[40:41], v75 offset0:206 offset1:239
	s_waitcnt lgkmcnt(0)
	v_cvt_pk_bf16_f32 v39, v40, v41
	v_lshl_add_u64 v[44:45], v[42:43], 0, v[2:3]
	ds_read2_b32 v[40:41], v75 offset0:16 offset1:49
	global_store_dwordx4 v[44:45], v[36:39], off
	v_or_b32_e32 v2, s0, v77
	v_lshlrev_b32_e32 v2, 12, v2
	s_waitcnt lgkmcnt(0)
	v_cvt_pk_bf16_f32 v36, v40, v41
	ds_read2_b32 v[38:39], v75 offset0:82 offset1:115
	s_waitcnt lgkmcnt(0)
	v_cvt_pk_bf16_f32 v37, v38, v39
	ds_read2_b32 v[38:39], v75 offset0:148 offset1:181
	s_waitcnt lgkmcnt(0)
	v_cvt_pk_bf16_f32 v38, v38, v39
	ds_read2_b32 v[40:41], v75 offset0:214 offset1:247
	s_waitcnt lgkmcnt(0)
	v_cvt_pk_bf16_f32 v39, v40, v41
	v_lshl_add_u64 v[44:45], v[42:43], 0, v[2:3]
	ds_read2_b32 v[40:41], v75 offset0:24 offset1:57
	global_store_dwordx4 v[44:45], v[36:39], off
	v_or_b32_e32 v2, s0, v78
	v_lshlrev_b32_e32 v2, 12, v2
	s_waitcnt lgkmcnt(0)
	v_cvt_pk_bf16_f32 v36, v40, v41
	ds_read2_b32 v[38:39], v75 offset0:90 offset1:123
	s_waitcnt lgkmcnt(0)
	v_cvt_pk_bf16_f32 v37, v38, v39
	ds_read2_b32 v[38:39], v75 offset0:156 offset1:189
	s_waitcnt lgkmcnt(0)
	v_cvt_pk_bf16_f32 v38, v38, v39
	ds_read2_b32 v[40:41], v75 offset0:222 offset1:255
	s_waitcnt lgkmcnt(0)
	v_cvt_pk_bf16_f32 v39, v40, v41
	v_lshl_add_u64 v[40:41], v[42:43], 0, v[2:3]
	global_store_dwordx4 v[40:41], v[36:39], off
	s_waitcnt lgkmcnt(0)
	v_readlane_b32 s77, v252, 2
	v_readlane_b32 s78, v252, 3
	v_readlane_b32 s79, v252, 4
	v_readlane_b32 s80, v252, 5
	v_readlane_b32 s81, v252, 6
	v_readlane_b32 s82, v252, 7
	v_readlane_b32 s83, v252, 8
	v_readlane_b32 s86, v252, 11
	v_readlane_b32 s87, v252, 12
	v_readlane_b32 s88, v252, 13
	v_readlane_b32 s89, v252, 14
	v_readlane_b32 s90, v252, 15
	v_readlane_b32 s91, v252, 16

.LBB0_109:
	s_andn2_b64 vcc, exec, s[0:1]
	s_cbranch_vccnz .LBB0_10
	s_mul_hi_i32 s0, s75, 0x2e8ba2e9
	s_lshr_b32 s1, s0, 31
	s_ashr_i32 s0, s0, 4
	s_add_i32 s0, s0, s1
	s_mul_i32 s2, s0, 0xfffff500
	s_mul_i32 s1, s0, 0xffffffa8
	s_add_i32 s10, s26, s2
	s_add_i32 s1, s75, s1
	s_add_i32 s2, s10, 0xfffffc00
	s_cmp_lt_i32 s1, 64
	s_cselect_b32 s2, s2, s10
	s_lshl_b32 s0, s0, 6
	v_or_b32_e32 v2, s0, v56
	s_ashr_i32 s3, s2, 31
	v_lshl_add_u64 v[36:37], s[2:3], 2, v[28:29]
	v_or_b32_e32 v33, 2, v2
	v_mad_i64_i32 v[40:41], s[2:3], v33, s74, v[36:37]
	v_or_b32_e32 v33, 4, v2
	v_mad_i64_i32 v[42:43], s[2:3], v33, s74, v[36:37]
	v_or_b32_e32 v33, 6, v2
	v_mad_i64_i32 v[44:45], s[2:3], v33, s74, v[36:37]
	v_or_b32_e32 v33, 8, v2
	v_mad_i64_i32 v[46:47], s[2:3], v33, s74, v[36:37]
	v_or_b32_e32 v33, 10, v2
	v_mad_i64_i32 v[48:49], s[2:3], v33, s74, v[36:37]
	v_or_b32_e32 v33, 12, v2
	v_mad_i64_i32 v[50:51], s[2:3], v33, s74, v[36:37]
	v_or_b32_e32 v33, 14, v2
	v_mad_i64_i32 v[38:39], s[2:3], v2, s74, v[36:37]
	v_mad_i64_i32 v[52:53], s[2:3], v33, s74, v[36:37]
	global_load_dword v33, v[38:39], off nt
	global_load_dword v35, v[40:41], off nt
	global_load_dword v54, v[42:43], off nt
	global_load_dword v55, v[44:45], off nt
	global_load_dword v79, v[46:47], off nt
	global_load_dword v80, v[48:49], off nt
	global_load_dword v81, v[50:51], off nt
	global_load_dword v82, v[52:53], off nt
	v_or_b32_e32 v38, 16, v2
	v_or_b32_e32 v40, 18, v2
	v_or_b32_e32 v42, 20, v2
	v_or_b32_e32 v44, 22, v2
	v_or_b32_e32 v46, 24, v2
	v_or_b32_e32 v48, 26, v2
	v_or_b32_e32 v50, 28, v2
	v_or_b32_e32 v52, 30, v2
	v_mad_i64_i32 v[38:39], s[2:3], v38, s74, v[36:37]
	v_mad_i64_i32 v[40:41], s[2:3], v40, s74, v[36:37]
	v_mad_i64_i32 v[42:43], s[2:3], v42, s74, v[36:37]
	v_mad_i64_i32 v[44:45], s[2:3], v44, s74, v[36:37]
	v_mad_i64_i32 v[46:47], s[2:3], v46, s74, v[36:37]
	v_mad_i64_i32 v[48:49], s[2:3], v48, s74, v[36:37]
	v_mad_i64_i32 v[50:51], s[2:3], v50, s74, v[36:37]
	v_mad_i64_i32 v[52:53], s[2:3], v52, s74, v[36:37]
	global_load_dword v83, v[38:39], off nt
	global_load_dword v84, v[40:41], off nt
	global_load_dword v85, v[42:43], off nt
	global_load_dword v86, v[44:45], off nt
	global_load_dword v87, v[46:47], off nt
	global_load_dword v88, v[48:49], off nt
	global_load_dword v89, v[50:51], off nt
	global_load_dword v90, v[52:53], off nt
	v_or_b32_e32 v38, 32, v2
	v_or_b32_e32 v40, 34, v2
	v_or_b32_e32 v42, 36, v2
	v_or_b32_e32 v44, 38, v2
	v_or_b32_e32 v46, 40, v2
	v_or_b32_e32 v48, 42, v2
	v_or_b32_e32 v50, 44, v2
	v_or_b32_e32 v52, 46, v2
	v_mad_i64_i32 v[38:39], s[2:3], v38, s74, v[36:37]
	v_mad_i64_i32 v[40:41], s[2:3], v40, s74, v[36:37]
	v_mad_i64_i32 v[42:43], s[2:3], v42, s74, v[36:37]
	v_mad_i64_i32 v[44:45], s[2:3], v44, s74, v[36:37]
	v_mad_i64_i32 v[46:47], s[2:3], v46, s74, v[36:37]
	v_mad_i64_i32 v[48:49], s[2:3], v48, s74, v[36:37]
	v_mad_i64_i32 v[50:51], s[2:3], v50, s74, v[36:37]
	v_mad_i64_i32 v[52:53], s[2:3], v52, s74, v[36:37]
	global_load_dword v91, v[38:39], off nt
	global_load_dword v92, v[40:41], off nt
	global_load_dword v93, v[42:43], off nt
	global_load_dword v94, v[44:45], off nt
	global_load_dword v95, v[46:47], off nt
	global_load_dword v96, v[48:49], off nt
	global_load_dword v97, v[50:51], off nt
	s_nop 0
	global_load_dword v52, v[52:53], off nt
	v_or_b32_e32 v38, 48, v2
	v_or_b32_e32 v40, 50, v2
	v_or_b32_e32 v42, 52, v2
	v_or_b32_e32 v44, 54, v2
	v_or_b32_e32 v46, 56, v2
	v_or_b32_e32 v48, 58, v2
	v_or_b32_e32 v50, 60, v2
	v_or_b32_e32 v2, 62, v2
	v_mad_i64_i32 v[38:39], s[2:3], v38, s74, v[36:37]
	v_mad_i64_i32 v[40:41], s[2:3], v40, s74, v[36:37]
	v_mad_i64_i32 v[42:43], s[2:3], v42, s74, v[36:37]
	v_mad_i64_i32 v[44:45], s[2:3], v44, s74, v[36:37]
	v_mad_i64_i32 v[46:47], s[2:3], v46, s74, v[36:37]
	v_mad_i64_i32 v[48:49], s[2:3], v48, s74, v[36:37]
	v_mad_i64_i32 v[50:51], s[2:3], v50, s74, v[36:37]
	v_mad_i64_i32 v[36:37], s[2:3], v2, s74, v[36:37]
	global_load_dword v2, v[38:39], off nt
	s_nop 0
	global_load_dword v38, v[40:41], off nt
	global_load_dword v39, v[42:43], off nt
	s_nop 0
	global_load_dword v40, v[44:45], off nt
	global_load_dword v41, v[46:47], off nt
	global_load_dword v42, v[48:49], off nt
	global_load_dword v43, v[50:51], off nt
	s_nop 0
	global_load_dword v36, v[36:37], off nt
	s_waitcnt vmcnt(30)
	ds_write2_b32 v58, v33, v35 offset1:66
	s_waitcnt vmcnt(28)
	ds_write2_b32 v58, v54, v55 offset0:132 offset1:198
	v_add_u32_e32 v33, 0x400, v58
	s_waitcnt vmcnt(26)
	ds_write2_b32 v33, v79, v80 offset0:8 offset1:74
	s_waitcnt vmcnt(24)
	ds_write2_b32 v33, v81, v82 offset0:140 offset1:206
	v_add_u32_e32 v33, 0x800, v58
	s_waitcnt vmcnt(22)
	ds_write2_b32 v33, v83, v84 offset0:16 offset1:82
	s_waitcnt vmcnt(20)
	ds_write2_b32 v33, v85, v86 offset0:148 offset1:214
	v_add_u32_e32 v33, 0xc00, v58
	s_waitcnt vmcnt(18)
	ds_write2_b32 v33, v87, v88 offset0:24 offset1:90
	s_waitcnt vmcnt(16)
	ds_write2_b32 v33, v89, v90 offset0:156 offset1:222
	v_add_u32_e32 v33, 0x1000, v58
	s_waitcnt vmcnt(14)
	ds_write2_b32 v33, v91, v92 offset0:32 offset1:98
	s_waitcnt vmcnt(12)
	ds_write2_b32 v33, v93, v94 offset0:164 offset1:230
	v_add_u32_e32 v33, 0x1400, v58
	s_waitcnt vmcnt(10)
	ds_write2_b32 v33, v95, v96 offset0:40 offset1:106
	s_waitcnt vmcnt(8)
	ds_write2_b32 v33, v97, v52 offset0:172 offset1:238
	v_add_u32_e32 v33, 0x1800, v58
	s_waitcnt vmcnt(6)
	ds_write2_b32 v33, v2, v38 offset0:48 offset1:114
	s_waitcnt vmcnt(4)
	ds_write2_b32 v33, v39, v40 offset0:180 offset1:246
	v_add_u32_e32 v2, 0x1c00, v58
	s_waitcnt vmcnt(2)
	ds_write2_b32 v2, v41, v42 offset0:56 offset1:122
	s_waitcnt vmcnt(0)
	ds_write2_b32 v2, v43, v36 offset0:188 offset1:254
	s_waitcnt lgkmcnt(0)
	ds_read2_b32 v[36:37], v75 offset1:33
	s_waitcnt lgkmcnt(0)
	v_cvt_pk_bf16_f32 v36, v36, v37
	ds_read2_b32 v[38:39], v75 offset0:66 offset1:99
	s_waitcnt lgkmcnt(0)
	v_cvt_pk_bf16_f32 v37, v38, v39
	ds_read2_b32 v[38:39], v75 offset0:132 offset1:165
	s_waitcnt lgkmcnt(0)
	v_cvt_pk_bf16_f32 v38, v38, v39
	ds_read2_b32 v[40:41], v75 offset0:198 offset1:231
	v_add_u32_e32 v2, s10, v74
	s_waitcnt lgkmcnt(0)
	v_cvt_pk_bf16_f32 v39, v40, v41
	v_add_u32_e32 v40, 0xfffffc00, v2
	s_ashr_i32 s1, s0, 31
	v_ashrrev_i32_e32 v41, 31, v40
	v_lshl_add_u64 v[42:43], s[0:1], 1, v[30:31]
	v_lshlrev_b64 v[40:41], 12, v[40:41]
	v_lshl_add_u64 v[40:41], v[42:43], 0, v[40:41]
	ds_read2_b32 v[44:45], v75 offset0:8 offset1:41
	global_store_dwordx4 v[40:41], v[36:39], off
	s_waitcnt lgkmcnt(0)
	s_nop 0
	v_cvt_pk_bf16_f32 v36, v44, v45
	ds_read2_b32 v[38:39], v75 offset0:74 offset1:107
	s_waitcnt lgkmcnt(0)
	v_cvt_pk_bf16_f32 v37, v38, v39
	ds_read2_b32 v[38:39], v75 offset0:140 offset1:173
	s_waitcnt lgkmcnt(0)
	v_cvt_pk_bf16_f32 v38, v38, v39
	ds_read2_b32 v[40:41], v75 offset0:206 offset1:239
	s_waitcnt lgkmcnt(0)
	v_cvt_pk_bf16_f32 v39, v40, v41
	v_add_u32_e32 v40, 0xfffffc08, v2
	v_ashrrev_i32_e32 v41, 31, v40
	v_lshlrev_b64 v[40:41], 12, v[40:41]
	v_lshl_add_u64 v[40:41], v[42:43], 0, v[40:41]
	ds_read2_b32 v[44:45], v75 offset0:16 offset1:49
	global_store_dwordx4 v[40:41], v[36:39], off
	s_waitcnt lgkmcnt(0)
	s_nop 0
	v_cvt_pk_bf16_f32 v36, v44, v45
	ds_read2_b32 v[38:39], v75 offset0:82 offset1:115
	s_waitcnt lgkmcnt(0)
	v_cvt_pk_bf16_f32 v37, v38, v39
	ds_read2_b32 v[38:39], v75 offset0:148 offset1:181
	s_waitcnt lgkmcnt(0)
	v_cvt_pk_bf16_f32 v38, v38, v39
	ds_read2_b32 v[40:41], v75 offset0:214 offset1:247
	s_waitcnt lgkmcnt(0)
	v_cvt_pk_bf16_f32 v39, v40, v41
	v_add_u32_e32 v40, 0xfffffc10, v2
	v_ashrrev_i32_e32 v41, 31, v40
	v_lshlrev_b64 v[40:41], 12, v[40:41]
	v_lshl_add_u64 v[40:41], v[42:43], 0, v[40:41]
	ds_read2_b32 v[44:45], v75 offset0:24 offset1:57
	global_store_dwordx4 v[40:41], v[36:39], off
	s_waitcnt lgkmcnt(0)
	s_nop 0
	v_cvt_pk_bf16_f32 v36, v44, v45
	ds_read2_b32 v[38:39], v75 offset0:90 offset1:123
	s_waitcnt lgkmcnt(0)
	v_cvt_pk_bf16_f32 v37, v38, v39
	ds_read2_b32 v[38:39], v75 offset0:156 offset1:189
	s_waitcnt lgkmcnt(0)
	v_cvt_pk_bf16_f32 v38, v38, v39
	ds_read2_b32 v[40:41], v75 offset0:222 offset1:255
	s_waitcnt lgkmcnt(0)
	v_cvt_pk_bf16_f32 v39, v40, v41
	v_add_u32_e32 v40, 0xfffffc18, v2
	v_ashrrev_i32_e32 v41, 31, v40
	v_lshlrev_b64 v[40:41], 12, v[40:41]
	v_lshl_add_u64 v[40:41], v[42:43], 0, v[40:41]
	global_store_dwordx4 v[40:41], v[36:39], off
	s_waitcnt lgkmcnt(0)
	s_branch .LBB0_10
